# dn_intra: per-head gate constants hoisted out of the unit loop, a/b gate rows prefetched one unit ahead, store-drain waits before the conv removed; scan state-update LDS reads issued ahead; K/V cache
# baseline (speedup 1.0000x reference)
; #define LAS __attribute__((address_space(3)))
; DI unsigned pk2(float lo, float hi) { f32x2 v = {lo, hi}; bf16x2_t b = __builtin_convertvector(v, bf16x2_t); return __builtin_bit_cast(unsigned, b); }
; DI float bf2f(bf16_t b) { return __uint_as_float(((unsigned)b) << 16); }
; DI int crow(int r, int hi) { return (r & 3) + 8 * (r >> 2) + 4 * hi; }
; #define MFMA32(a, b, c) __builtin_amdgcn_mfma_f32_32x32x16_bf16((a), (b), (c), 0, 0, 0)
; DI void lds_barrier() { asm volatile("s_waitcnt lgkmcnt(0)" ::: "memory"); __builtin_amdgcn_s_barrier(); asm volatile("" ::: "memory"); }
; DI void dn_scan(const Params& p, LAS unsigned char* L, int tid, int wave, int lane, int bid, int G) {
;     ...
;         f32x16 vacc, oacc;
; #pragma unroll
;         for (int e = 0; e < 16; ++e) { vacc[e] = bf2f(*(const LAS bf16_t*)(L + SC_U + (ib * 32 + crow(e, hi)) * 272 + (db * 32 + n31) * 2)); oacc[e] = 0.f; }
; #pragma unroll 2
;         for (int ks = 0; ks < 8; ++ks) {
;             const bf16x8 bs = *(const LAS bf16x8*)(L + SC_ST + (db * 32 + n31) * 272 + ks * 32 + hi * 16);
;             const bf16x8 aw = *(const LAS bf16x8*)(L + SC_W + (ib * 32 + n31) * 272 + ks * 32 + hi * 16);
;             const bf16x8 aq = *(const LAS bf16x8*)(L + SC_QG + (ib * 32 + n31) * 272 + ks * 32 + hi * 16);
;             vacc = MFMA32(aw, bs, vacc); oacc = MFMA32(aq, bs, oacc);
;         }
; #pragma unroll
;         for (int g = 0; g < 4; ++g) { u32x2 w2; w2.x = pk2(vacc[4 * g], vacc[4 * g + 1]); w2.y = pk2(vacc[4 * g + 2], vacc[4 * g + 3]);
;             *(LAS u32x2*)(L + SC_VNT + (db * 32 + n31) * 144 + (ib * 32 + 8 * g + 4 * hi) * 2) = w2; }
;         lds_barrier();
.LBB0_645:
	v_add_u32_e32 v218, 0x13800, v133
	ds_read_b128 v[138:141], v218
	ds_read_b128 v[142:145], v132 offset:17408
	ds_read_b128 v[146:149], v132
	ds_read_b128 v[150:153], v218 offset:32
	ds_read_b128 v[154:157], v132 offset:17440
	ds_read_b128 v[158:161], v132 offset:32
	ds_read_b128 v[162:165], v218 offset:64
	ds_read_b128 v[166:169], v132 offset:17472
	ds_read_b128 v[170:173], v132 offset:64
	ds_read_b128 v[174:177], v218 offset:96
	ds_read_b128 v[178:181], v132 offset:17504
	ds_read_b128 v[182:185], v132 offset:96
	s_waitcnt lgkmcnt(9)
	v_mfma_f32_32x32x16_bf16 v[32:47], v[142:145], v[138:141], v[32:47]
	v_mfma_f32_32x32x16_bf16 v[48:63], v[146:149], v[138:141], v[48:63]
	ds_read_b128 v[138:141], v218 offset:128
	ds_read_b128 v[142:145], v132 offset:17536
	ds_read_b128 v[146:149], v132 offset:128
	s_waitcnt lgkmcnt(9)
	v_mfma_f32_32x32x16_bf16 v[32:47], v[154:157], v[150:153], v[32:47]
	v_mfma_f32_32x32x16_bf16 v[48:63], v[158:161], v[150:153], v[48:63]
	ds_read_b128 v[150:153], v218 offset:160
	ds_read_b128 v[154:157], v132 offset:17568
	ds_read_b128 v[158:161], v132 offset:160
	s_waitcnt lgkmcnt(9)
	v_mfma_f32_32x32x16_bf16 v[32:47], v[166:169], v[162:165], v[32:47]
	v_mfma_f32_32x32x16_bf16 v[48:63], v[170:173], v[162:165], v[48:63]
	ds_read_b128 v[162:165], v218 offset:192
	ds_read_b128 v[166:169], v132 offset:17600
	ds_read_b128 v[170:173], v132 offset:192
	s_waitcnt lgkmcnt(9)
	v_mfma_f32_32x32x16_bf16 v[32:47], v[178:181], v[174:177], v[32:47]
	v_mfma_f32_32x32x16_bf16 v[48:63], v[182:185], v[174:177], v[48:63]
	ds_read_b128 v[174:177], v218 offset:224
	ds_read_b128 v[178:181], v132 offset:17632
	ds_read_b128 v[182:185], v132 offset:224
	s_waitcnt lgkmcnt(9)
	v_mfma_f32_32x32x16_bf16 v[32:47], v[142:145], v[138:141], v[32:47]
	v_mfma_f32_32x32x16_bf16 v[48:63], v[146:149], v[138:141], v[48:63]
	s_waitcnt lgkmcnt(6)
	v_mfma_f32_32x32x16_bf16 v[32:47], v[154:157], v[150:153], v[32:47]
	v_mfma_f32_32x32x16_bf16 v[48:63], v[158:161], v[150:153], v[48:63]
	s_waitcnt lgkmcnt(3)
	v_mfma_f32_32x32x16_bf16 v[32:47], v[166:169], v[162:165], v[32:47]
	v_mfma_f32_32x32x16_bf16 v[48:63], v[170:173], v[162:165], v[48:63]
	s_waitcnt lgkmcnt(0)
	v_mfma_f32_32x32x16_bf16 v[32:47], v[178:181], v[174:177], v[32:47]
	v_mfma_f32_32x32x16_bf16 v[48:63], v[182:185], v[174:177], v[48:63]
	s_nop 1
	s_nop 10
	v_cvt_pk_bf16_f32 v48, v48, v49
	v_cvt_pk_bf16_f32 v49, v50, v51
	v_cvt_pk_bf16_f32 v50, v52, v53
	v_cvt_pk_bf16_f32 v51, v54, v55
	ds_write2_b64 v134, v[48:49], v[50:51] offset1:2
	v_cvt_pk_bf16_f32 v48, v56, v57
	v_cvt_pk_bf16_f32 v49, v58, v59
	v_cvt_pk_bf16_f32 v50, v60, v61
	v_cvt_pk_bf16_f32 v51, v62, v63
	ds_write2_b64 v134, v[48:49], v[50:51] offset0:4 offset1:6
	s_waitcnt lgkmcnt(0)
	s_barrier
; #define LAS __attribute__((address_space(3)))
; #define MFMA32(a, b, c) __builtin_amdgcn_mfma_f32_32x32x16_bf16((a), (b), (c), 0, 0, 0)
; DI void lds_barrier() { asm volatile("s_waitcnt lgkmcnt(0)" ::: "memory"); __builtin_amdgcn_s_barrier(); asm volatile("" ::: "memory"); }
; #define SC_WRITE_ST() do { _Pragma("unroll") for (int k2 = 0; k2 < 2; ++k2) { const int kb = ib * 2 + k2; _Pragma("unroll") for (int g = 0; g < 4; ++g) { u32x2 w2; w2.x = pk2(sacc[k2][4 * g], sacc[k2][4 * g + 1]); w2.y = pk2(sacc[k2][4 * g + 2], sacc[k2][4 * g + 3]); \
;         *(LAS u32x2*)(L + SC_ST + (db * 32 + n31) * 272 + (kb * 32 + 8 * g + 4 * hi) * 2) = w2; } } } while (0)
; DI void dn_scan(const Params& p, LAS unsigned char* L, int tid, int wave, int lane, int bid, int G) {
;     ...
; #pragma unroll
;         for (int ks = 0; ks < 4; ++ks) {
;             const bf16x8 bv = *(const LAS bf16x8*)(L + SC_VNT + (db * 32 + n31) * 144 + ks * 32 + hi * 16);
;             const bf16x8 aa = *(const LAS bf16x8*)(L + SC_AT + (ib * 32 + n31) * 144 + ks * 32 + hi * 16);
;             oacc = MFMA32(aa, bv, oacc);
;         }
; #pragma unroll
;         for (int k2 = 0; k2 < 2; ++k2) { const int kb = ib * 2 + k2;
; #pragma unroll
;             for (int e = 0; e < 16; ++e) sacc[k2][e] *= glast;
; #pragma unroll
;             for (int ks = 0; ks < 4; ++ks) {
;                 const bf16x8 bv = *(const LAS bf16x8*)(L + SC_VNT + (db * 32 + n31) * 144 + ks * 32 + hi * 16);
;                 const bf16x8 ak = *(const LAS bf16x8*)(L + SC_KGT + (kb * 32 + n31) * 144 + ks * 32 + hi * 16);
;                 sacc[k2] = MFMA32(ak, bv, sacc[k2]);
;             } }
;         lds_barrier();
;         SC_WRITE_ST();
;         if (c + 1 < nsteps) SC_STORE();
	v_add_u32_e32 v138, v130, v129
	ds_read_b128 v[48:51], v138
	ds_read_b128 v[52:55], v138 offset:32
	ds_read_b128 v[154:157], v136 offset:44032
	ds_read_b128 v[158:161], v136 offset:44064
	ds_read_b128 v[60:63], v138 offset:64
	ds_read_b128 v[138:141], v138 offset:96
	ds_read_b128 v[162:165], v136 offset:44096
	ds_read_b128 v[166:169], v136 offset:44128
	ds_read_b128 v[170:173], v136 offset:48640
	ds_read_b128 v[174:177], v136 offset:48672
	ds_read_b128 v[178:181], v136 offset:48704
	ds_read_b128 v[182:185], v136 offset:48736
	v_pk_mul_f32 v[0:1], v[118:119], v[0:1] op_sel_hi:[0,1]
	v_pk_mul_f32 v[2:3], v[118:119], v[2:3] op_sel_hi:[0,1]
	v_pk_mul_f32 v[4:5], v[118:119], v[4:5] op_sel_hi:[0,1]
	v_pk_mul_f32 v[6:7], v[118:119], v[6:7] op_sel_hi:[0,1]
	v_pk_mul_f32 v[8:9], v[118:119], v[8:9] op_sel_hi:[0,1]
	v_pk_mul_f32 v[10:11], v[118:119], v[10:11] op_sel_hi:[0,1]
	v_pk_mul_f32 v[12:13], v[118:119], v[12:13] op_sel_hi:[0,1]
	v_pk_mul_f32 v[14:15], v[118:119], v[14:15] op_sel_hi:[0,1]
	v_pk_mul_f32 v[16:17], v[118:119], v[16:17] op_sel_hi:[0,1]
	v_pk_mul_f32 v[18:19], v[118:119], v[18:19] op_sel_hi:[0,1]
	s_waitcnt lgkmcnt(8)
	v_mfma_f32_32x32x16_bf16 v[0:15], v[154:157], v[48:51], v[0:15]
	v_mul_f32_e64 v20, v118, v20
	v_mul_f32_e64 v21, v118, v21
	v_mul_f32_e64 v22, v118, v22
	v_mul_f32_e64 v23, v118, v23
	v_mul_f32_e64 v24, v118, v24
	v_mul_f32_e64 v25, v118, v25
	v_pk_mul_f32 v[26:27], v[118:119], v[26:27] op_sel_hi:[0,1]
	v_pk_mul_f32 v[28:29], v[118:119], v[28:29] op_sel_hi:[0,1]
	v_pk_mul_f32 v[30:31], v[118:119], v[30:31] op_sel_hi:[0,1]
	s_and_b64 vcc, exec, s[4:5]
	v_mfma_f32_32x32x16_bf16 v[0:15], v[158:161], v[52:55], v[0:15]
	s_waitcnt lgkmcnt(4)
	v_mfma_f32_32x32x16_bf16 v[0:15], v[162:165], v[60:63], v[0:15]
	v_mfma_f32_32x32x16_bf16 v[0:15], v[166:169], v[138:141], v[0:15]
	s_waitcnt lgkmcnt(0)
	ds_read_b128 v[56:59], v135 offset:34816
	ds_read_b128 v[142:145], v135 offset:34848
	ds_read_b128 v[146:149], v135 offset:34880
	ds_read_b128 v[150:153], v135 offset:34912
	v_mfma_f32_32x32x16_bf16 v[16:31], v[170:173], v[48:51], v[16:31]
	v_mfma_f32_32x32x16_bf16 v[16:31], v[174:177], v[52:55], v[16:31]
	v_mfma_f32_32x32x16_bf16 v[16:31], v[178:181], v[60:63], v[16:31]
	v_mfma_f32_32x32x16_bf16 v[16:31], v[182:185], v[138:141], v[16:31]
	s_waitcnt lgkmcnt(0)
	s_barrier
	s_waitcnt lgkmcnt(0)
	v_mfma_f32_32x32x16_bf16 v[32:47], v[56:59], v[48:51], v[32:47]
	v_cvt_pk_bf16_f32 v48, v0, v1
	v_cvt_pk_bf16_f32 v49, v2, v3
	v_cvt_pk_bf16_f32 v50, v4, v5
	v_cvt_pk_bf16_f32 v51, v6, v7
	ds_write2_b64 v127, v[48:49], v[50:51] offset1:2
	v_cvt_pk_bf16_f32 v48, v8, v9
	v_cvt_pk_bf16_f32 v49, v10, v11
	v_mfma_f32_32x32x16_bf16 v[32:47], v[142:145], v[52:55], v[32:47]
	v_cvt_pk_bf16_f32 v50, v12, v13
	v_cvt_pk_bf16_f32 v51, v14, v15
	ds_write2_b64 v127, v[48:49], v[50:51] offset0:4 offset1:6
	v_cvt_pk_bf16_f32 v48, v16, v17
	v_cvt_pk_bf16_f32 v49, v18, v19
	v_cvt_pk_bf16_f32 v50, v20, v21
	v_cvt_pk_bf16_f32 v51, v22, v23
	v_mfma_f32_32x32x16_bf16 v[32:47], v[146:149], v[60:63], v[32:47]
	ds_write2_b64 v127, v[48:49], v[50:51] offset0:8 offset1:10
	v_cvt_pk_bf16_f32 v48, v24, v25
	v_cvt_pk_bf16_f32 v49, v26, v27
	v_cvt_pk_bf16_f32 v50, v28, v29
	v_cvt_pk_bf16_f32 v51, v30, v31
	ds_write2_b64 v127, v[48:49], v[50:51] offset0:12 offset1:14
	v_mfma_f32_32x32x16_bf16 v[32:47], v[150:153], v[138:141], v[32:47]
	s_cbranch_vccz .LBB0_641
	s_waitcnt vmcnt(0)
	ds_write_b128 v121, v[66:69]
	ds_write_b128 v121, v[70:73] offset:17408
	ds_write_b128 v121, v[74:77] offset:62464
	ds_write_b16 v122, v78 offset:44032
	ds_write_b16_d16_hi v122, v78 offset:44176
	ds_write_b16 v122, v79 offset:44320
	ds_write_b16_d16_hi v122, v79 offset:44464
	ds_write_b16 v122, v80 offset:44608
	ds_write_b16_d16_hi v122, v80 offset:44752
	ds_write_b16 v122, v81 offset:44896
	ds_write_b16_d16_hi v122, v81 offset:45040
	ds_write_b128 v123, v[82:85]
	ds_write_b128 v123, v[86:89] offset:17408
	ds_write_b128 v123, v[90:93] offset:62464
	ds_write_b16 v124, v94 offset:44032
	ds_write_b16_d16_hi v124, v94 offset:44176
	ds_write_b16 v124, v95 offset:44320
	ds_write_b16_d16_hi v124, v95 offset:44464
	ds_write_b16 v124, v96 offset:44608
	ds_write_b16_d16_hi v124, v96 offset:44752
	ds_write_b16 v124, v97 offset:44896
	ds_write_b16_d16_hi v124, v97 offset:45040
	ds_write_b128 v126, v[98:101] offset:34816
	s_branch .LBB0_641

; DI u32x4 v8_pack(const V8& v) { u32x4 w; w.x = pk2(v.a.x, v.a.y); w.y = pk2(v.a.z, v.a.w); w.z = pk2(v.b.x, v.b.y); w.w = pk2(v.b.z, v.b.w); return w; }
; DI void sb_cache_convert(const Params& p, LAS float* scr  , int gtid, int NT, int gw, int NGW, int lane) {
;     ...
;     for (int it = gtid; it < 8 * PAST * D / 8; it += NT) { const int c8 = it & 127, rp = it >> 7, b = rp >> 11, pos = rp & 2047;
;         V8 v; v.a = __builtin_nontemporal_load((const f32x4*)(ck + (size_t)rp * D + c8 * 8)); v.b = __builtin_nontemporal_load((const f32x4*)(ck + (size_t)rp * D + c8 * 8 + 4)); *(u32x4*)(KS + ((size_t)b * LK + pos) * D + c8 * 8) = v8_pack(v); }
.LBB0_807:
	v_ashrrev_i32_e32 v2, 7, v0
	v_ashrrev_i32_e32 v3, 31, v2
	v_and_b32_e32 v136, 0x7ff, v2
	v_lshlrev_b64 v[2:3], 12, v[2:3]
	v_and_b32_e32 v12, 0x3f8, v1
	v_lshl_add_u64 v[2:3], s[70:71], 0, v[2:3]
	v_lshlrev_b32_e32 v64, 2, v12
	v_lshl_add_u64 v[6:7], v[2:3], 0, v[64:65]
	global_load_dwordx4 v[104:107], v[6:7], off offset:16 nt
	global_load_dwordx4 v[108:111], v[6:7], off nt
	v_ashrrev_i32_e32 v137, 18, v0
	v_lshlrev_b32_e32 v138, 1, v12
	v_add_u32_e32 v0, s44, v0
	v_add_u32_e32 v1, s22, v1
	v_ashrrev_i32_e32 v2, 7, v0
	v_ashrrev_i32_e32 v3, 31, v2
	v_and_b32_e32 v139, 0x7ff, v2
	v_lshlrev_b64 v[2:3], 12, v[2:3]
	v_and_b32_e32 v12, 0x3f8, v1
	v_lshl_add_u64 v[2:3], s[70:71], 0, v[2:3]
	v_lshlrev_b32_e32 v64, 2, v12
	v_lshl_add_u64 v[6:7], v[2:3], 0, v[64:65]
	global_load_dwordx4 v[112:115], v[6:7], off offset:16 nt
	global_load_dwordx4 v[116:119], v[6:7], off nt
	v_ashrrev_i32_e32 v140, 18, v0
	v_lshlrev_b32_e32 v141, 1, v12
	v_add_u32_e32 v0, s44, v0
	v_add_u32_e32 v1, s22, v1
	v_ashrrev_i32_e32 v2, 7, v0
	v_ashrrev_i32_e32 v3, 31, v2
	v_and_b32_e32 v142, 0x7ff, v2
	v_lshlrev_b64 v[2:3], 12, v[2:3]
	v_and_b32_e32 v12, 0x3f8, v1
	v_lshl_add_u64 v[2:3], s[70:71], 0, v[2:3]
	v_lshlrev_b32_e32 v64, 2, v12
	v_lshl_add_u64 v[6:7], v[2:3], 0, v[64:65]
	global_load_dwordx4 v[120:123], v[6:7], off offset:16 nt
	global_load_dwordx4 v[124:127], v[6:7], off nt
	v_ashrrev_i32_e32 v143, 18, v0
	v_lshlrev_b32_e32 v144, 1, v12
	v_add_u32_e32 v0, s44, v0
	v_add_u32_e32 v1, s22, v1
	v_ashrrev_i32_e32 v2, 7, v0
	v_ashrrev_i32_e32 v3, 31, v2
	v_and_b32_e32 v145, 0x7ff, v2
	v_lshlrev_b64 v[2:3], 12, v[2:3]
	v_and_b32_e32 v12, 0x3f8, v1
	v_lshl_add_u64 v[2:3], s[70:71], 0, v[2:3]
	v_lshlrev_b32_e32 v64, 2, v12
	v_lshl_add_u64 v[6:7], v[2:3], 0, v[64:65]
	global_load_dwordx4 v[128:131], v[6:7], off offset:16 nt
	global_load_dwordx4 v[132:135], v[6:7], off nt
	v_ashrrev_i32_e32 v146, 18, v0
	v_lshlrev_b32_e32 v147, 1, v12
	v_add_u32_e32 v0, s44, v0
	v_add_u32_e32 v1, s22, v1
	v_cmp_lt_i32_e32 vcc, s23, v0
	s_or_b64 s[6:7], vcc, s[6:7]
	s_waitcnt vmcnt(6)
	v_cvt_pk_bf16_f32 v6, v108, v109
	v_cvt_pk_bf16_f32 v7, v110, v111
	v_cvt_pk_bf16_f32 v8, v104, v105
	v_cvt_pk_bf16_f32 v9, v106, v107
	v_mul_i32_i24_e32 v2, 0x840, v137
	v_ashrrev_i32_e32 v3, 31, v2
	v_mov_b32_e32 v10, v136
	v_mov_b32_e32 v11, v65
	v_lshl_add_u64 v[2:3], v[2:3], 0, v[10:11]
	v_lshlrev_b64 v[2:3], 11, v[2:3]
	v_lshl_add_u64 v[2:3], s[4:5], 0, v[2:3]
	v_mov_b32_e32 v64, v138
	v_lshl_add_u64 v[2:3], v[2:3], 0, v[64:65]
	global_store_dwordx4 v[2:3], v[6:9], off
	s_nop 1
	s_waitcnt vmcnt(5)
	v_cvt_pk_bf16_f32 v6, v116, v117
	v_cvt_pk_bf16_f32 v7, v118, v119
	v_cvt_pk_bf16_f32 v8, v112, v113
	v_cvt_pk_bf16_f32 v9, v114, v115
	v_mul_i32_i24_e32 v2, 0x840, v140
	v_ashrrev_i32_e32 v3, 31, v2
	v_mov_b32_e32 v10, v139
	v_mov_b32_e32 v11, v65
	v_lshl_add_u64 v[2:3], v[2:3], 0, v[10:11]
	v_lshlrev_b64 v[2:3], 11, v[2:3]
	v_lshl_add_u64 v[2:3], s[4:5], 0, v[2:3]
	v_mov_b32_e32 v64, v141
	v_lshl_add_u64 v[2:3], v[2:3], 0, v[64:65]
	global_store_dwordx4 v[2:3], v[6:9], off
	s_nop 1
	s_waitcnt vmcnt(4)
	v_cvt_pk_bf16_f32 v6, v124, v125
	v_cvt_pk_bf16_f32 v7, v126, v127
	v_cvt_pk_bf16_f32 v8, v120, v121
	v_cvt_pk_bf16_f32 v9, v122, v123
	v_mul_i32_i24_e32 v2, 0x840, v143
	v_ashrrev_i32_e32 v3, 31, v2
	v_mov_b32_e32 v10, v142
	v_mov_b32_e32 v11, v65
	v_lshl_add_u64 v[2:3], v[2:3], 0, v[10:11]
	v_lshlrev_b64 v[2:3], 11, v[2:3]
	v_lshl_add_u64 v[2:3], s[4:5], 0, v[2:3]
	v_mov_b32_e32 v64, v144
	v_lshl_add_u64 v[2:3], v[2:3], 0, v[64:65]
	global_store_dwordx4 v[2:3], v[6:9], off
	s_nop 1
	s_waitcnt vmcnt(3)
	v_cvt_pk_bf16_f32 v6, v132, v133
	v_cvt_pk_bf16_f32 v7, v134, v135
	v_cvt_pk_bf16_f32 v8, v128, v129
	v_cvt_pk_bf16_f32 v9, v130, v131
	v_mul_i32_i24_e32 v2, 0x840, v146
	v_ashrrev_i32_e32 v3, 31, v2
	v_mov_b32_e32 v10, v145
	v_mov_b32_e32 v11, v65
	v_lshl_add_u64 v[2:3], v[2:3], 0, v[10:11]
	v_lshlrev_b64 v[2:3], 11, v[2:3]
	v_lshl_add_u64 v[2:3], s[4:5], 0, v[2:3]
	v_mov_b32_e32 v64, v147
	v_lshl_add_u64 v[2:3], v[2:3], 0, v[64:65]
	global_store_dwordx4 v[2:3], v[6:9], off
	s_nop 1
	s_andn2_b64 exec, exec, s[6:7]
	s_cbranch_execnz .LBB0_807

; DI void sb_cache_convert(const Params& p, LAS float* scr  , int gtid, int NT, int gw, int NGW, int lane) {
;     ...
;     for (int it = gw; it < 8 * 16 * 32; it += NGW) { const int pb = it & 31, h = (it >> 5) & 15, b = it >> 9, p0 = pb * 64;
; #pragma unroll 8
;         for (int i = 0; i < 64; ++i) scr[i * 65 + lane] = __builtin_nontemporal_load(cv + ((size_t)b * PAST + p0 + i) * D + h * 64 + lane);
;         asm volatile("s_waitcnt lgkmcnt(0)" ::: "memory");
.LBB0_811:
	v_lshl_add_u64 v[6:7], v[2:3], 0, s[6:7]
	global_load_dword v150, v[6:7], off nt
	v_add_co_u32_e32 v8, vcc, 0x1000, v6
	s_nop 1
	v_addc_co_u32_e32 v9, vcc, 0, v7, vcc
	global_load_dword v151, v[8:9], off nt
	v_add_co_u32_e32 v8, vcc, 0x2000, v6
	s_nop 1
	v_addc_co_u32_e32 v9, vcc, 0, v7, vcc
	global_load_dword v152, v[8:9], off nt
	v_add_co_u32_e32 v8, vcc, 0x3000, v6
	s_nop 1
	v_addc_co_u32_e32 v9, vcc, 0, v7, vcc
	global_load_dword v153, v[8:9], off nt
	v_add_co_u32_e32 v8, vcc, 0x4000, v6
	s_nop 1
	v_addc_co_u32_e32 v9, vcc, 0, v7, vcc
	global_load_dword v154, v[8:9], off nt
	v_add_co_u32_e32 v8, vcc, 0x5000, v6
	s_nop 1
	v_addc_co_u32_e32 v9, vcc, 0, v7, vcc
	global_load_dword v155, v[8:9], off nt
	v_add_co_u32_e32 v8, vcc, 0x6000, v6
	s_nop 1
	v_addc_co_u32_e32 v9, vcc, 0, v7, vcc
	global_load_dword v156, v[8:9], off nt
	v_add_co_u32_e32 v8, vcc, 0x7000, v6
	s_nop 1
	v_addc_co_u32_e32 v9, vcc, 0, v7, vcc
	global_load_dword v157, v[8:9], off nt
	s_add_u32 s6, s6, 0x8000
	s_addc_u32 s7, s7, 0
	v_lshl_add_u64 v[6:7], v[2:3], 0, s[6:7]
	global_load_dword v158, v[6:7], off nt
	v_add_co_u32_e32 v8, vcc, 0x1000, v6
	s_nop 1
	v_addc_co_u32_e32 v9, vcc, 0, v7, vcc
	global_load_dword v159, v[8:9], off nt
	v_add_co_u32_e32 v8, vcc, 0x2000, v6
	s_nop 1
	v_addc_co_u32_e32 v9, vcc, 0, v7, vcc
	global_load_dword v160, v[8:9], off nt
	v_add_co_u32_e32 v8, vcc, 0x3000, v6
	s_nop 1
	v_addc_co_u32_e32 v9, vcc, 0, v7, vcc
	global_load_dword v161, v[8:9], off nt
	v_add_co_u32_e32 v8, vcc, 0x4000, v6
	s_nop 1
	v_addc_co_u32_e32 v9, vcc, 0, v7, vcc
	global_load_dword v162, v[8:9], off nt
	v_add_co_u32_e32 v8, vcc, 0x5000, v6
	s_nop 1
	v_addc_co_u32_e32 v9, vcc, 0, v7, vcc
	global_load_dword v163, v[8:9], off nt
	v_add_co_u32_e32 v8, vcc, 0x6000, v6
	s_nop 1
	v_addc_co_u32_e32 v9, vcc, 0, v7, vcc
	global_load_dword v164, v[8:9], off nt
	v_add_co_u32_e32 v8, vcc, 0x7000, v6
	s_nop 1
	v_addc_co_u32_e32 v9, vcc, 0, v7, vcc
	global_load_dword v165, v[8:9], off nt
	s_add_u32 s6, s6, 0x8000
	s_addc_u32 s7, s7, 0
	v_lshl_add_u64 v[6:7], v[2:3], 0, s[6:7]
	global_load_dword v166, v[6:7], off nt
	v_add_co_u32_e32 v8, vcc, 0x1000, v6
	s_nop 1
	v_addc_co_u32_e32 v9, vcc, 0, v7, vcc
	global_load_dword v167, v[8:9], off nt
	v_add_co_u32_e32 v8, vcc, 0x2000, v6
	s_nop 1
	v_addc_co_u32_e32 v9, vcc, 0, v7, vcc
	global_load_dword v168, v[8:9], off nt
	v_add_co_u32_e32 v8, vcc, 0x3000, v6
	s_nop 1
	v_addc_co_u32_e32 v9, vcc, 0, v7, vcc
	global_load_dword v169, v[8:9], off nt
	v_add_co_u32_e32 v8, vcc, 0x4000, v6
	s_nop 1
	v_addc_co_u32_e32 v9, vcc, 0, v7, vcc
	global_load_dword v170, v[8:9], off nt
	v_add_co_u32_e32 v8, vcc, 0x5000, v6
	s_nop 1
	v_addc_co_u32_e32 v9, vcc, 0, v7, vcc
	global_load_dword v171, v[8:9], off nt
	v_add_co_u32_e32 v8, vcc, 0x6000, v6
	s_nop 1
	v_addc_co_u32_e32 v9, vcc, 0, v7, vcc
	global_load_dword v172, v[8:9], off nt
	v_add_co_u32_e32 v8, vcc, 0x7000, v6
	s_nop 1
	v_addc_co_u32_e32 v9, vcc, 0, v7, vcc
	global_load_dword v173, v[8:9], off nt
	s_add_u32 s6, s6, 0x8000
	s_addc_u32 s7, s7, 0
	v_lshl_add_u64 v[6:7], v[2:3], 0, s[6:7]
	global_load_dword v174, v[6:7], off nt
	v_add_co_u32_e32 v8, vcc, 0x1000, v6
	s_nop 1
	v_addc_co_u32_e32 v9, vcc, 0, v7, vcc
	global_load_dword v175, v[8:9], off nt
	v_add_co_u32_e32 v8, vcc, 0x2000, v6
	s_nop 1
	v_addc_co_u32_e32 v9, vcc, 0, v7, vcc
	global_load_dword v176, v[8:9], off nt
	v_add_co_u32_e32 v8, vcc, 0x3000, v6
	s_nop 1
	v_addc_co_u32_e32 v9, vcc, 0, v7, vcc
	global_load_dword v177, v[8:9], off nt
	v_add_co_u32_e32 v8, vcc, 0x4000, v6
	s_nop 1
	v_addc_co_u32_e32 v9, vcc, 0, v7, vcc
	global_load_dword v178, v[8:9], off nt
	v_add_co_u32_e32 v8, vcc, 0x5000, v6
	s_nop 1
	v_addc_co_u32_e32 v9, vcc, 0, v7, vcc
	global_load_dword v179, v[8:9], off nt
	v_add_co_u32_e32 v8, vcc, 0x6000, v6
	s_nop 1
	v_addc_co_u32_e32 v9, vcc, 0, v7, vcc
	global_load_dword v180, v[8:9], off nt
	v_add_co_u32_e32 v8, vcc, 0x7000, v6
	s_nop 1
	v_addc_co_u32_e32 v9, vcc, 0, v7, vcc
	global_load_dword v181, v[8:9], off nt
	s_add_u32 s6, s6, 0x8000
	s_addc_u32 s7, s7, 0
	v_add_u32_e32 v11, 0x400, v5
	s_waitcnt vmcnt(30)
	ds_write2_b32 v5, v150, v151 offset1:65
	s_waitcnt vmcnt(28)
	ds_write2_b32 v5, v152, v153 offset0:130 offset1:195
	s_waitcnt vmcnt(26)
	ds_write2_b32 v11, v154, v155 offset0:4 offset1:69
	s_waitcnt vmcnt(24)
	ds_write2_b32 v11, v156, v157 offset0:134 offset1:199
	v_add_u32_e32 v5, 0x820, v5
	v_add_u32_e32 v11, 0x400, v5
	s_waitcnt vmcnt(22)
	ds_write2_b32 v5, v158, v159 offset1:65
	s_waitcnt vmcnt(20)
	ds_write2_b32 v5, v160, v161 offset0:130 offset1:195
	s_waitcnt vmcnt(18)
	ds_write2_b32 v11, v162, v163 offset0:4 offset1:69
	s_waitcnt vmcnt(16)
	ds_write2_b32 v11, v164, v165 offset0:134 offset1:199
	v_add_u32_e32 v5, 0x820, v5
	v_add_u32_e32 v11, 0x400, v5
	s_waitcnt vmcnt(14)
	ds_write2_b32 v5, v166, v167 offset1:65
	s_waitcnt vmcnt(12)
	ds_write2_b32 v5, v168, v169 offset0:130 offset1:195
	s_waitcnt vmcnt(10)
	ds_write2_b32 v11, v170, v171 offset0:4 offset1:69
	s_waitcnt vmcnt(8)
	ds_write2_b32 v11, v172, v173 offset0:134 offset1:199
	v_add_u32_e32 v5, 0x820, v5
	v_add_u32_e32 v11, 0x400, v5
	s_waitcnt vmcnt(6)
	ds_write2_b32 v5, v174, v175 offset1:65
	s_waitcnt vmcnt(4)
	ds_write2_b32 v5, v176, v177 offset0:130 offset1:195
	s_waitcnt vmcnt(2)
	ds_write2_b32 v11, v178, v179 offset0:4 offset1:69
	s_waitcnt vmcnt(0)
	ds_write2_b32 v11, v180, v181 offset0:134 offset1:199
	v_add_u32_e32 v5, 0x820, v5
	s_cmp_eq_u32 s6, 0x40000
	s_cbranch_scc0 .LBB0_811
; #define LAS __attribute__((address_space(3)))
; DI unsigned pk2(float lo, float hi) { f32x2 v = {lo, hi}; bf16x2_t b = __builtin_convertvector(v, bf16x2_t); return __builtin_bit_cast(unsigned, b); }
; DI void sb_cache_convert(const Params& p, LAS float* scr  , int gtid, int NT, int gw, int NGW, int lane) {
;     ...
;         asm volatile("s_waitcnt lgkmcnt(0)" ::: "memory");
;         bf16_t* dst = VTS + ((size_t)(b * 16 + h) * 64 + lane) * LK + p0;
; #pragma unroll
;         for (int c = 0; c < 8; ++c) { const LAS float* s = scr + (8 * c) * 65 + lane; u32x4 o; o.x = pk2(s[0], s[65]); o.y = pk2(s[130], s[195]); o.z = pk2(s[260], s[325]); o.w = pk2(s[390], s[455]); *(u32x4*)(dst + 8 * c) = o; }
;         asm volatile("s_waitcnt lgkmcnt(0)" ::: "memory");
	s_waitcnt lgkmcnt(0)
	ds_read2_b32 v[6:7], v4 offset1:65
	ds_read2_b32 v[8:9], v4 offset0:130 offset1:195
	s_and_b32 s5, s8, 15
	s_lshl_b32 s4, s4, 4
	s_or_b32 s4, s4, s5
	s_ashr_i32 s6, s4, 31
	v_lshl_or_b32 v5, s4, 6, v102
	v_mov_b64_e32 v[2:3], s[0:1]
	s_movk_i32 s4, 0x1080
	v_mad_u64_u32 v[2:3], s[4:5], v5, s4, v[2:3]
	v_add_u32_e32 v5, 0x400, v4
	s_waitcnt lgkmcnt(0)
	v_cvt_pk_bf16_f32 v6, v6, v7
	v_cvt_pk_bf16_f32 v7, v8, v9
	ds_read2_b32 v[8:9], v5 offset0:4 offset1:69
	ds_read2_b32 v[10:11], v5 offset0:134 offset1:199
	s_lshl_b32 s4, s12, 7
	v_mad_i32_i24 v3, s6, v237, v3
	s_and_b32 s8, s4, 0xf80
	v_lshl_add_u64 v[2:3], v[2:3], 0, s[8:9]
	s_waitcnt lgkmcnt(1)
	v_cvt_pk_bf16_f32 v8, v8, v9
	s_waitcnt lgkmcnt(0)
	v_cvt_pk_bf16_f32 v9, v10, v11
	global_store_dwordx4 v[2:3], v[6:9], off
	v_add_u32_e32 v5, 0x800, v4
	ds_read2_b32 v[6:7], v5 offset0:8 offset1:73
	ds_read2_b32 v[8:9], v5 offset0:138 offset1:203
	v_add_u32_e32 v5, 0xc00, v4
	ds_read2_b32 v[10:11], v5 offset0:142 offset1:207
	s_add_i32 s12, s12, s37
	s_waitcnt lgkmcnt(0)
	v_cvt_pk_bf16_f32 v6, v6, v7
	v_cvt_pk_bf16_f32 v7, v8, v9
	ds_read2_b32 v[8:9], v5 offset0:12 offset1:77
	v_add_u32_e32 v5, 0x1000, v4
	s_add_i32 s10, s10, s44
	s_cmpk_gt_i32 s12, 0xfff
	s_waitcnt lgkmcnt(0)
	v_cvt_pk_bf16_f32 v8, v8, v9
	v_cvt_pk_bf16_f32 v9, v10, v11
	global_store_dwordx4 v[2:3], v[6:9], off offset:16
	ds_read2_b32 v[6:7], v5 offset0:16 offset1:81
	ds_read2_b32 v[8:9], v5 offset0:146 offset1:211
	v_add_u32_e32 v5, 0x1400, v4
	ds_read2_b32 v[10:11], v5 offset0:150 offset1:215
	s_waitcnt lgkmcnt(0)
	v_cvt_pk_bf16_f32 v6, v6, v7
	v_cvt_pk_bf16_f32 v7, v8, v9
	ds_read2_b32 v[8:9], v5 offset0:20 offset1:85
	v_add_u32_e32 v5, 0x1800, v4
	s_waitcnt lgkmcnt(0)
	v_cvt_pk_bf16_f32 v8, v8, v9
	v_cvt_pk_bf16_f32 v9, v10, v11
	global_store_dwordx4 v[2:3], v[6:9], off offset:32
	ds_read2_b32 v[6:7], v5 offset0:24 offset1:89
	ds_read2_b32 v[8:9], v5 offset0:154 offset1:219
	v_add_u32_e32 v5, 0x1c00, v4
	ds_read2_b32 v[10:11], v5 offset0:158 offset1:223
	s_waitcnt lgkmcnt(0)
	v_cvt_pk_bf16_f32 v6, v6, v7
	v_cvt_pk_bf16_f32 v7, v8, v9
	ds_read2_b32 v[8:9], v5 offset0:28 offset1:93
	v_add_u32_e32 v5, 0x2000, v4
	s_waitcnt lgkmcnt(0)
	v_cvt_pk_bf16_f32 v8, v8, v9
	v_cvt_pk_bf16_f32 v9, v10, v11
	global_store_dwordx4 v[2:3], v[6:9], off offset:48
	ds_read2_b32 v[6:7], v5 offset0:32 offset1:97
	ds_read2_b32 v[8:9], v5 offset0:162 offset1:227
	v_add_u32_e32 v5, 0x2400, v4
	ds_read2_b32 v[10:11], v5 offset0:166 offset1:231
	s_waitcnt lgkmcnt(0)
	v_cvt_pk_bf16_f32 v6, v6, v7
	v_cvt_pk_bf16_f32 v7, v8, v9
	ds_read2_b32 v[8:9], v5 offset0:36 offset1:101
	v_add_u32_e32 v5, 0x2800, v4
	s_waitcnt lgkmcnt(0)
	v_cvt_pk_bf16_f32 v8, v8, v9
	v_cvt_pk_bf16_f32 v9, v10, v11
	global_store_dwordx4 v[2:3], v[6:9], off offset:64
	ds_read2_b32 v[6:7], v5 offset0:40 offset1:105
	ds_read2_b32 v[8:9], v5 offset0:170 offset1:235
	v_add_u32_e32 v5, 0x2c00, v4
	ds_read2_b32 v[10:11], v5 offset0:174 offset1:239
	s_waitcnt lgkmcnt(0)
	v_cvt_pk_bf16_f32 v6, v6, v7
	v_cvt_pk_bf16_f32 v7, v8, v9
	ds_read2_b32 v[8:9], v5 offset0:44 offset1:109
	v_add_u32_e32 v5, 0x3000, v4
	s_waitcnt lgkmcnt(0)
	v_cvt_pk_bf16_f32 v8, v8, v9
	v_cvt_pk_bf16_f32 v9, v10, v11
	global_store_dwordx4 v[2:3], v[6:9], off offset:80
	ds_read2_b32 v[6:7], v5 offset0:48 offset1:113
	ds_read2_b32 v[8:9], v5 offset0:178 offset1:243
	v_add_u32_e32 v5, 0x3400, v4
	ds_read2_b32 v[10:11], v5 offset0:182 offset1:247
	s_waitcnt lgkmcnt(0)
	v_cvt_pk_bf16_f32 v6, v6, v7
	v_cvt_pk_bf16_f32 v7, v8, v9
	ds_read2_b32 v[8:9], v5 offset0:52 offset1:117
	v_add_u32_e32 v5, 0x3800, v4
	s_waitcnt lgkmcnt(0)
	v_cvt_pk_bf16_f32 v8, v8, v9
	v_cvt_pk_bf16_f32 v9, v10, v11
	global_store_dwordx4 v[2:3], v[6:9], off offset:96
	ds_read2_b32 v[6:7], v5 offset0:56 offset1:121
	ds_read2_b32 v[8:9], v5 offset0:186 offset1:251
	v_add_u32_e32 v5, 0x3c00, v4
	ds_read2_b32 v[10:11], v5 offset0:190 offset1:255
	s_waitcnt lgkmcnt(0)
	v_cvt_pk_bf16_f32 v6, v6, v7
	v_cvt_pk_bf16_f32 v7, v8, v9
	ds_read2_b32 v[8:9], v5 offset0:60 offset1:125
	s_waitcnt lgkmcnt(0)
	v_cvt_pk_bf16_f32 v8, v8, v9
	v_cvt_pk_bf16_f32 v9, v10, v11
	global_store_dwordx4 v[2:3], v[6:9], off offset:112
	s_waitcnt lgkmcnt(0)
	s_cbranch_scc0 .LBB0_810

; #define LAS __attribute__((address_space(3)))
; DI void rowinfo(int row, int& s, int& b, int& t) { if (row < MP) { s = 0; b = row >> 12; t = row & 4095; } else { const int r = row - MP; s = 1; b = r >> 6; t = r & 63; } }
; DI void lds_barrier() { asm volatile("s_waitcnt lgkmcnt(0)" ::: "memory"); __builtin_amdgcn_s_barrier(); asm volatile("" ::: "memory"); }
; DI void dn_intra(const Params& p, LAS unsigned char* L, int tid_in, int wave, int bid, int G, bool dry) {
;     bf16_t* PRE = (bf16_t*)(p.ws + WS_PRE); bf16_t* Wb = (bf16_t*)(p.ws + WS_W); bf16_t* ATT = (bf16_t*)(p.out + O_VP);
;     const bf16_t* HALO = (const bf16_t*)(p.ws + WS_HALO); const float* AB = (const float*)(p.ws + WS_AB); float* GL = (float*)(p.ws + WS_GL);
;     const float* convw = p.in[14]; const float* stc = p.in[3];
;     LAS float* gcs = (LAS float*)(L + DN_GC); LAS float* betas = (LAS float*)(L + DN_BETA);
;     LAS float* Mm = (LAS float*)(L + DN_MM); LAS float* RHS = (LAS float*)(L + DN_RHS);
;     const int h = bid & 7, ngrp = (G >> 3) > 0 ? (G >> 3) : 1;
;     LAS float* CW = (LAS float*)(L + DN_CW);
;     for (int i = tid_in; i < 4 * 384; i += 512) { const int j = i / 384, c = i % 384; CW[i] = convw[(size_t)j * DNQ + (c >> 7) * 1024 + h * 128 + (c & 127)]; }
;     lds_barrier();
;     ...
;     u32x4 xr[3][4][2];
;     if ((bid >> 3) < NSEG) DN_PREFETCH(bid >> 3, tid_in);
;     for (int seg = (bid >> 3); seg < NSEG; seg += ngrp) {
;         if ((G >> 3) == 0 && (bid != 0)) break;
;         const int u = seg * 8 + h, row0 = seg * 64;
;         int s, b, t0; rowinfo(row0, s, b, t0);
;         int tid = tid_in; asm volatile("" : "+v"(tid)); int lane = tid & 63;
;         const int r = tid >> 3, sub = tid & 7;
;         if (wave == 0) {
;             const float a = AB[(size_t)(row0 + lane) * 16 + h], bq = AB[(size_t)(row0 + lane) * 16 + 8 + h];
.LBB0_909:
	s_waitcnt vmcnt(0)
	s_andn2_b64 vcc, exec, s[0:1]
	s_cbranch_vccnz .LBB0_1112
	s_cmp_lg_u32 s14, 0
	v_readlane_b32 s4, v253, 15
	s_cselect_b64 s[0:1], -1, 0
	v_readlane_b32 s5, v253, 16
	s_and_b64 s[0:1], s[4:5], s[0:1]
	s_and_b64 vcc, exec, s[0:1]
	s_cbranch_vccnz .LBB0_1112
	s_lshl_b32 s4, s12, 2
	s_add_u32 s0, s28, s4
	s_addc_u32 s1, s29, 0
	s_add_u32 s50, s0, 0x1c00000
	s_addc_u32 s51, s1, 0
	s_lshl_b32 s14, s12, 7
	s_lshl_b32 s5, s12, 8
	v_and_b32_e64 v0, s15, 1
	v_and_b32_e64 v1, 2, s15
	s_add_u32 s52, s26, s5
	v_cmp_ne_u32_e32 vcc, 0, v1
	v_cmp_eq_u32_e64 s[0:1], 0, v0
	s_addc_u32 s53, s27, 0
	s_or_b64 s[54:55], s[0:1], vcc
	s_add_u32 s58, s28, s5
	v_cmp_lt_u32_e64 vcc, s15, 4
	v_mov_b32_e32 v1, 0x4400
	v_mov_b32_e32 v2, 0xcc00
	v_lshlrev_b32_e32 v183, 5, v0
	v_mov_b32_e32 v0, s85
	s_addc_u32 s59, s29, 0
	v_cmp_ne_u32_e64 s[48:49], s15, 0
	v_cmp_gt_u32_e64 s[56:57], s15, 3
	v_cndmask_b32_e32 v1, v1, v2, vcc
	v_lshlrev_b32_e64 v2, 4, s15
	v_lshl_add_u32 v186, s15, 7, v0
	s_add_u32 s15, s30, 0x10e70000
	s_addc_u32 s16, s31, 0
	s_add_u32 s17, s28, 0x1f00000
	s_addc_u32 s18, s29, 0
	v_readlane_b32 s60, v253, 27
	v_readlane_b32 s61, v253, 28
	v_readlane_b32 s62, v253, 29
	v_readlane_b32 s63, v253, 30
	v_readlane_b32 s64, v253, 31
	v_readlane_b32 s65, v253, 32
	v_readlane_b32 s66, v253, 33
	v_readlane_b32 s67, v253, 34
	v_readlane_b32 s68, v253, 35
	v_readlane_b32 s69, v253, 36
	v_readlane_b32 s70, v253, 37
	v_readlane_b32 s71, v253, 38
	v_readlane_b32 s72, v253, 39
	v_readlane_b32 s73, v253, 40
	v_readlane_b32 s74, v253, 41
	v_readlane_b32 s75, v253, 42
	s_add_u32 s22, s60, s4
	s_addc_u32 s23, s61, 0
	v_readlane_b32 s60, v254, 7
	v_readlane_b32 s74, v254, 21
	v_readlane_b32 s76, v254, 40
	v_readlane_b32 s75, v254, 22
	s_add_u32 s34, s74, s4
	v_and_b32_e32 v149, 32, v2
	v_add_u32_e32 v185, 0, v1
	v_readlane_b32 s88, v254, 42
	v_readlane_b32 s77, v254, 41
	s_addc_u32 s35, s75, 0
	v_readlane_b32 s61, v254, 8
	v_readlane_b32 s62, v254, 9
	v_readlane_b32 s63, v254, 10
	v_readlane_b32 s64, v254, 11
	v_readlane_b32 s65, v254, 12
	v_readlane_b32 s66, v254, 13
	v_readlane_b32 s67, v254, 14
	v_readlane_b32 s68, v254, 15
	v_readlane_b32 s69, v254, 16
	v_readlane_b32 s70, v254, 17
	v_readlane_b32 s71, v254, 18
	v_readlane_b32 s72, v254, 19
	v_readlane_b32 s73, v254, 20
	global_load_dword v220, v65, s[22:23]
	global_load_dword v221, v65, s[34:35]
	v_and_b32_e32 v222, 63, v148
	s_lshl_b32 vcc_lo, s13, 6
	v_or_b32_e32 v222, vcc_lo, v222
	v_ashrrev_i32_e32 v223, 31, v222
	v_lshlrev_b64 v[222:223], 6, v[222:223]
	v_lshl_add_u64 v[222:223], s[50:51], 0, v[222:223]
	global_load_dword v224, v[222:223], off
	global_load_dword v225, v[222:223], off offset:32
	s_waitcnt vmcnt(0)
	s_branch .LBB0_913

; DI void dn_intra(const Params& p, LAS unsigned char* L, int tid_in, int wave, int bid, int G, bool dry) {
;     ...
;         if (wave == 0) {
;             const float a = AB[(size_t)(row0 + lane) * 16 + h], bq = AB[(size_t)(row0 + lane) * 16 + 8 + h];
;             const float beta = 1.f / (1.f + expf(-bq));
;             const float x = a + p.in[16][h]; const float spx = fmaxf(x, 0.f) + log1pf(expf(-fabsf(x)));
;             float g = -expf(p.in[15][h]) * spx;
; #pragma unroll
;             for (int o = 1; o < 64; o <<= 1) { const float v = __shfl_up(g, o); if (lane >= o) g += v; }
;             gcs[lane] = g; betas[lane] = beta;
.LBB0_915:
	v_and_b32_e32 v0, 63, v187
	v_or_b32_e32 v2, s19, v0
	v_ashrrev_i32_e32 v3, 31, v2
	v_lshlrev_b64 v[2:3], 6, v[2:3]
	v_lshl_add_u64 v[2:3], s[50:51], 0, v[2:3]
	v_mov_b32_e32 v4, v224
	v_mov_b32_e32 v1, v225
	s_mov_b32 s1, 0x42ce8ed0
	s_mov_b32 s4, 0xc2b17218
	v_mov_b32_e32 v15, 0x7f800000
	s_mov_b32 s0, 0xb2a5705f
	v_mov_b32_e32 v66, v238
	v_mov_b32_e32 v168, v228
	s_waitcnt lgkmcnt(0)
	v_mul_f32_e32 v2, 0xbfb8aa3b, v1
	v_fma_f32 v3, v1, s80, -v2
	v_rndne_f32_e32 v5, v2
	v_fmac_f32_e32 v3, 0xb2a5705f, v1
	v_sub_f32_e32 v2, v2, v5
	v_add_f32_e32 v2, v2, v3
	v_exp_f32_e32 v2, v2
	v_cvt_i32_f32_e32 v3, v5
	v_cmp_nlt_f32_e32 vcc, s1, v1
	v_ldexp_f32 v2, v2, v3
	s_nop 0
	v_cndmask_b32_e32 v2, 0, v2, vcc
	v_cmp_ngt_f32_e32 vcc, s4, v1
	s_nop 1
	v_cndmask_b32_e32 v1, v15, v2, vcc
	v_mov_b32_e32 v2, v220
	v_add_f32_e32 v1, 1.0, v1
	v_add_f32_e32 v2, v4, v2
	v_mul_f32_e64 v3, |v2|, s80
	v_fma_f32 v5, |v2|, s80, -v3
	v_rndne_f32_e32 v6, v3
	v_fma_f32 v5, |v2|, s0, v5
	v_sub_f32_e32 v3, v3, v6
	v_add_f32_e32 v3, v3, v5
	v_exp_f32_e32 v3, v3
	v_cvt_i32_f32_e32 v5, v6
	v_cmp_ngt_f32_e64 vcc, |v2|, s1
	v_max_f32_e32 v4, 0, v2
	s_mov_b32 s0, 0x3f2aaaab
	v_ldexp_f32 v3, v3, v5
	v_cndmask_b32_e32 v3, 0, v3, vcc
	v_cmp_nlt_f32_e64 vcc, |v2|, s4
	s_nop 1
	v_cndmask_b32_e32 v5, v15, v3, vcc
	v_add_f32_e32 v6, 1.0, v5
	v_add_f32_e32 v2, -1.0, v6
	v_sub_f32_e32 v3, v2, v6
	v_add_f32_e32 v3, 1.0, v3
	v_sub_f32_e32 v2, v5, v2
	v_add_f32_e32 v7, v2, v3
	v_frexp_mant_f32_e32 v2, v6
	v_cmp_gt_f32_e32 vcc, s0, v2
	v_cvt_f64_f32_e32 v[2:3], v6
	v_frexp_exp_i32_f64_e32 v2, v[2:3]
	v_subbrev_co_u32_e32 v2, vcc, 0, v2, vcc
	v_sub_u32_e32 v3, 0, v2
	v_ldexp_f32 v6, v6, v3
	v_ldexp_f32 v3, v7, v3
	v_add_f32_e32 v7, -1.0, v6
	v_add_f32_e32 v8, 1.0, v7
	v_sub_f32_e32 v8, v6, v8
	v_add_f32_e32 v8, v3, v8
	v_add_f32_e32 v9, v7, v8
	v_sub_f32_e32 v7, v7, v9
	v_add_f32_e32 v7, v8, v7
	v_add_f32_e32 v8, 1.0, v6
	v_add_f32_e32 v10, -1.0, v8
	v_sub_f32_e32 v6, v6, v10
	v_add_f32_e32 v3, v3, v6
	v_add_f32_e32 v6, v8, v3
	v_sub_f32_e32 v8, v8, v6
	v_add_f32_e32 v3, v3, v8
	v_rcp_f32_e32 v8, v6
	v_cvt_f32_i32_e32 v2, v2
	s_mov_b32 s0, 0x7f800000
	v_cmp_neq_f32_e32 vcc, s0, v5
	v_mul_f32_e32 v10, v9, v8
	v_mul_f32_e32 v11, v6, v10
	v_fma_f32 v12, v10, v6, -v11
	v_fmac_f32_e32 v12, v10, v3
	v_add_f32_e32 v13, v11, v12
	v_sub_f32_e32 v14, v9, v13
	v_sub_f32_e32 v9, v9, v14
	v_sub_f32_e32 v11, v13, v11
	v_sub_f32_e32 v9, v9, v13
	v_add_f32_e32 v7, v7, v9
	v_sub_f32_e32 v9, v11, v12
	v_add_f32_e32 v7, v9, v7
	v_add_f32_e32 v9, v14, v7
	v_mul_f32_e32 v11, v8, v9
	v_mul_f32_e32 v12, v6, v11
	v_fma_f32 v6, v11, v6, -v12
	v_fmac_f32_e32 v6, v11, v3
	v_sub_f32_e32 v3, v14, v9
	v_add_f32_e32 v3, v7, v3
	v_add_f32_e32 v7, v12, v6
	v_sub_f32_e32 v13, v9, v7
	v_sub_f32_e32 v9, v9, v13
	v_sub_f32_e32 v12, v7, v12
	v_sub_f32_e32 v7, v9, v7
	v_add_f32_e32 v3, v3, v7
	v_sub_f32_e32 v6, v12, v6
	v_add_f32_e32 v3, v6, v3
	v_add_f32_e32 v6, v10, v11
	v_add_f32_e32 v3, v13, v3
	v_sub_f32_e32 v7, v6, v10
	v_mul_f32_e32 v3, v8, v3
	v_sub_f32_e32 v7, v11, v7
	v_add_f32_e32 v3, v7, v3
	v_mul_f32_e32 v10, 0x3f317218, v2
	v_add_f32_e32 v7, v6, v3
	v_fma_f32 v11, v2, s2, -v10
	v_mul_f32_e32 v8, v7, v7
	v_mov_b32_e32 v9, 0x3ecc95a3
	v_fmac_f32_e32 v11, 0xb102e308, v2
	v_sub_f32_e32 v2, v7, v6
	v_fmamk_f32 v9, v8, 0x3e9b6dac, v9
	v_sub_f32_e32 v2, v3, v2
	v_add_f32_e32 v3, v10, v11
	v_fmaak_f32 v9, v8, v9, 0x3f2aaada
	v_sub_f32_e32 v6, v3, v10
	v_ldexp_f32 v10, v7, 1
	v_mul_f32_e32 v7, v7, v8
	v_mul_f32_e32 v7, v7, v9
	v_add_f32_e32 v8, v10, v7
	v_sub_f32_e32 v9, v8, v10
	v_ldexp_f32 v2, v2, 1
	v_sub_f32_e32 v7, v7, v9
	v_add_f32_e32 v2, v2, v7
	v_add_f32_e32 v7, v8, v2
	v_sub_f32_e32 v8, v7, v8
	v_sub_f32_e32 v2, v2, v8
	v_add_f32_e32 v8, v3, v7
	v_sub_f32_e32 v9, v8, v3
	v_sub_f32_e32 v10, v8, v9
	v_sub_f32_e32 v6, v11, v6
	v_sub_f32_e32 v3, v3, v10
	v_sub_f32_e32 v7, v7, v9
	v_add_f32_e32 v3, v7, v3
	v_add_f32_e32 v7, v6, v2
	v_sub_f32_e32 v9, v7, v6
	v_sub_f32_e32 v10, v7, v9
	v_sub_f32_e32 v6, v6, v10
	v_sub_f32_e32 v2, v2, v9
	v_add_f32_e32 v3, v7, v3
	v_add_f32_e32 v2, v2, v6
	v_add_f32_e32 v6, v8, v3
	v_sub_f32_e32 v7, v6, v8
	v_sub_f32_e32 v3, v3, v7
	v_add_f32_e32 v2, v2, v3
	v_mov_b32_e32 v3, v221
	v_add_f32_e32 v2, v6, v2
	s_mov_b32 s0, 0x33800000
	v_cndmask_b32_e32 v2, v15, v2, vcc
	v_cmp_lt_f32_e64 vcc, |v5|, s0
	s_mov_b32 s0, 0x3fb8aa3b
	s_nop 0
	v_cndmask_b32_e32 v2, v2, v5, vcc
	v_add_f32_e32 v2, v4, v2
	v_mul_f32_e32 v4, 0x3fb8aa3b, v3
	v_fma_f32 v5, v3, s0, -v4
	v_rndne_f32_e32 v6, v4
	v_fmac_f32_e32 v5, 0x32a5705f, v3
	v_sub_f32_e32 v4, v4, v6
	v_add_f32_e32 v4, v4, v5
	v_exp_f32_e32 v4, v4
	v_cvt_i32_f32_e32 v5, v6
	s_mov_b32 s0, 0xc2ce8ed0
	v_cmp_ngt_f32_e32 vcc, s0, v3
	s_mov_b32 s0, 0x42b17218
	v_ldexp_f32 v4, v4, v5
	v_cndmask_b32_e32 v4, 0, v4, vcc
	v_cmp_nlt_f32_e32 vcc, s0, v3
	v_add_u32_e32 v5, -1, v228
	s_nop 0
	v_cndmask_b32_e32 v3, v15, v4, vcc
	v_cmp_lt_i32_e32 vcc, v5, v238
	v_mul_f32_e64 v4, v2, -v3
	s_nop 0
	v_cndmask_b32_e32 v5, v5, v228, vcc
	v_lshlrev_b32_e32 v5, 2, v5
	ds_bpermute_b32 v5, v5, v4
	v_cmp_eq_u32_e32 vcc, 0, v0
	s_waitcnt lgkmcnt(0)
	v_fma_f32 v2, v2, -v3, v5
	v_add_u32_e32 v3, -2, v228
	v_cndmask_b32_e32 v2, v2, v4, vcc
	v_cmp_lt_i32_e32 vcc, v3, v238
	s_nop 1
	v_cndmask_b32_e32 v3, v3, v228, vcc
	v_lshlrev_b32_e32 v3, 2, v3
	ds_bpermute_b32 v3, v3, v2
	v_cmp_gt_u32_e32 vcc, 2, v0
	s_waitcnt lgkmcnt(0)
	v_add_f32_e32 v3, v2, v3
	v_cndmask_b32_e32 v2, v3, v2, vcc
	v_add_u32_e32 v3, -4, v228
	v_cmp_lt_i32_e32 vcc, v3, v238
	s_nop 1
	v_cndmask_b32_e32 v3, v3, v228, vcc
	v_lshlrev_b32_e32 v3, 2, v3
	ds_bpermute_b32 v3, v3, v2
	v_cmp_gt_u32_e32 vcc, 4, v0
	s_waitcnt lgkmcnt(0)
	v_add_f32_e32 v3, v2, v3
	v_cndmask_b32_e32 v2, v3, v2, vcc
	v_add_u32_e32 v3, -8, v228
	v_cmp_lt_i32_e32 vcc, v3, v238
	s_nop 1
	v_cndmask_b32_e32 v3, v3, v228, vcc
	v_lshlrev_b32_e32 v3, 2, v3
	ds_bpermute_b32 v3, v3, v2
	v_cmp_gt_u32_e32 vcc, 8, v0
	s_waitcnt lgkmcnt(0)
	v_add_f32_e32 v3, v2, v3
	v_cndmask_b32_e32 v2, v3, v2, vcc
	v_add_u32_e32 v3, -16, v228
	v_cmp_lt_i32_e32 vcc, v3, v238
	s_nop 1
	v_cndmask_b32_e32 v3, v3, v228, vcc
	v_lshlrev_b32_e32 v3, 2, v3
	ds_bpermute_b32 v3, v3, v2
	v_cmp_gt_u32_e32 vcc, 16, v0
	s_waitcnt lgkmcnt(0)
	v_add_f32_e32 v3, v2, v3
	v_cndmask_b32_e32 v2, v3, v2, vcc
	v_subrev_u32_e32 v3, 32, v228
	v_cmp_lt_i32_e32 vcc, v3, v238
	s_nop 1
	v_cndmask_b32_e32 v3, v3, v228, vcc
	v_lshlrev_b32_e32 v3, 2, v3
	ds_bpermute_b32 v3, v3, v2
	v_cmp_gt_u32_e32 vcc, 32, v0
	v_lshl_add_u32 v0, v0, 2, 0
	s_waitcnt lgkmcnt(0)
	v_add_f32_e32 v3, v2, v3
	v_cndmask_b32_e32 v2, v3, v2, vcc
	v_div_scale_f32 v3, s[0:1], v1, v1, 1.0
	v_rcp_f32_e32 v4, v3
	s_nop 0
	v_fma_f32 v5, -v3, v4, 1.0
	v_fmac_f32_e32 v4, v5, v4
	v_div_scale_f32 v5, vcc, 1.0, v1, 1.0
	v_mul_f32_e32 v6, v5, v4
	v_fma_f32 v7, -v3, v6, v5
	v_fmac_f32_e32 v6, v7, v4
	v_fma_f32 v3, -v3, v6, v5
	v_div_fmas_f32 v3, v3, v4, v6
	v_div_fixup_f32 v1, v3, v1, 1.0
	v_add_u32_e32 v3, 0x21400, v0
	v_add_u32_e32 v0, 0x21500, v0
	ds_write_b32 v3, v2
	ds_write_b32 v0, v1
; #define LAS __attribute__((address_space(3)))
; DI V8 v8_from_bf(u32x4 w) { V8 r; r.a = (f32x4){bflo(w.x), bfhi(w.x), bflo(w.y), bfhi(w.y)}; r.b = (f32x4){bflo(w.z), bfhi(w.z), bflo(w.w), bfhi(w.w)}; return r; }
; DI float silu_f(float y) { return y * __builtin_amdgcn_rcpf(1.f + __builtin_amdgcn_exp2f(-1.4426950408889634f * y)); }
; DI void dn_intra(const Params& p, LAS unsigned char* L, int tid_in, int wave, int bid, int G, bool dry) {
;     ...
;         float qv[16], kv[16], vv[16]; float rq = 0.f, rk = 0.f;
; #pragma unroll
;         for (int part = 0; part < 3; ++part) {
;             float y[16];
; #pragma unroll
;             for (int e = 0; e < 16; ++e) y[e] = 0.f;
; #pragma unroll
;             for (int j = 0; j < 4; ++j) {
;                 const V8 x0 = v8_from_bf(xr[part][j][0]), x1 = v8_from_bf(xr[part][j][1]);
;                 const LAS float* wq = CW + j * 384 + part * 128 + sub * 16;
;                 const f32x4 wa = *(const LAS f32x4*)wq, wb = *(const LAS f32x4*)(wq + 4), wc = *(const LAS f32x4*)(wq + 8), wd = *(const LAS f32x4*)(wq + 12);
; #pragma unroll
;                 for (int e = 0; e < 4; ++e) { y[e] += wa[e] * x0.a[e]; y[4 + e] += wb[e] * x0.b[e]; y[8 + e] += wc[e] * x1.a[e]; y[12 + e] += wd[e] * x1.b[e]; }
;             }
;             float ss = 0.f;
; #pragma unroll
;             for (int e = 0; e < 16; ++e) { y[e] = silu_f(y[e]); ss += y[e] * y[e]; }
;             if (part < 2) { ss += __shfl_xor(ss, 1); ss += __shfl_xor(ss, 2); ss += __shfl_xor(ss, 4); }
.LBB0_916:
	v_and_b32_e32 v64, 7, v187
	v_lshlrev_b32_e32 v188, 6, v64
	v_add_u32_e32 v0, 0, v188
	v_add_u32_e32 v182, 0x21600, v0
	ds_read_b128 v[12:15], v182
	ds_read_b128 v[128:131], v182 offset:16
	ds_read_b128 v[144:147], v182 offset:32
	ds_read_b128 v[150:153], v182 offset:48
	ds_read_b128 v[8:11], v182 offset:1536
	ds_read_b128 v[124:127], v182 offset:1552
	ds_read_b128 v[140:143], v182 offset:1568
	ds_read_b128 v[154:157], v182 offset:1584
	ds_read_b128 v[4:7], v182 offset:3072
	ds_read_b128 v[120:123], v182 offset:3088
	ds_read_b128 v[136:139], v182 offset:3104
	ds_read_b128 v[158:161], v182 offset:3120
	ds_read_b128 v[0:3], v182 offset:4608
	ds_read_b128 v[116:119], v182 offset:4624
	ds_read_b128 v[132:135], v182 offset:4640
	ds_read_b128 v[162:165], v182 offset:4656
	s_waitcnt lgkmcnt(0)
	v_lshlrev_b32_e32 v166, 16, v23
	v_and_b32_e32 v167, 0xffff0000, v23
	v_pk_fma_f32 v[152:153], v[152:153], v[166:167], 0 op_sel_hi:[1,1,0]
	v_lshlrev_b32_e32 v166, 16, v31
	v_and_b32_e32 v167, 0xffff0000, v31
	v_pk_fma_f32 v[152:153], v[156:157], v[166:167], v[152:153]
	v_lshlrev_b32_e32 v156, 16, v39
	v_and_b32_e32 v157, 0xffff0000, v39
	v_pk_fma_f32 v[152:153], v[160:161], v[156:157], v[152:153]
	v_lshlrev_b32_e32 v156, 16, v47
	v_and_b32_e32 v157, 0xffff0000, v47
	v_pk_fma_f32 v[152:153], v[164:165], v[156:157], v[152:153]
	v_xor_b32_e32 v170, 1, v168
	v_mul_f32_e32 v67, 0xbfb8aa3b, v152
	v_mul_f32_e32 v156, 0xbfb8aa3b, v153
	v_exp_f32_e32 v67, v67
	v_exp_f32_e32 v156, v156
	v_add_u32_e32 v169, 64, v66
	v_cmp_lt_i32_e32 vcc, v170, v169
	v_add_f32_e32 v66, 1.0, v67
	v_add_f32_e32 v67, 1.0, v156
	v_cndmask_b32_e32 v156, v168, v170, vcc
	v_lshlrev_b32_e32 v170, 2, v156
	v_lshlrev_b32_e32 v156, 16, v21
	v_and_b32_e32 v157, 0xffff0000, v21
	v_pk_fma_f32 v[146:147], v[146:147], v[156:157], 0 op_sel_hi:[1,1,0]
	v_lshlrev_b32_e32 v156, 16, v29
	v_and_b32_e32 v157, 0xffff0000, v29
	v_pk_fma_f32 v[142:143], v[142:143], v[156:157], v[146:147]
	v_lshlrev_b32_e32 v146, 16, v37
	v_and_b32_e32 v147, 0xffff0000, v37
	v_pk_fma_f32 v[138:139], v[138:139], v[146:147], v[142:143]
	v_lshlrev_b32_e32 v142, 16, v45
	v_and_b32_e32 v143, 0xffff0000, v45
	v_pk_fma_f32 v[142:143], v[134:135], v[142:143], v[138:139]
	v_rcp_f32_e32 v66, v66
	v_mul_f32_e32 v134, 0xbfb8aa3b, v142
	v_exp_f32_e32 v138, v134
	v_mul_f32_e32 v134, 0xbfb8aa3b, v143
	v_exp_f32_e32 v139, v134
	v_rcp_f32_e32 v67, v67
	v_add_f32_e32 v138, 1.0, v138
	v_rcp_f32_e32 v146, v138
	v_add_f32_e32 v147, 1.0, v139
	v_lshlrev_b32_e32 v138, 16, v20
	v_and_b32_e32 v139, 0xffff0000, v20
	v_pk_fma_f32 v[138:139], v[144:145], v[138:139], 0 op_sel_hi:[1,1,0]
	v_lshlrev_b32_e32 v144, 16, v28
	v_and_b32_e32 v145, 0xffff0000, v28
	v_pk_fma_f32 v[138:139], v[140:141], v[144:145], v[138:139]
	v_lshlrev_b32_e32 v140, 16, v36
	v_and_b32_e32 v141, 0xffff0000, v36
	v_pk_fma_f32 v[136:137], v[136:137], v[140:141], v[138:139]
	v_lshlrev_b32_e32 v138, 16, v44
	v_and_b32_e32 v139, 0xffff0000, v44
	v_pk_fma_f32 v[136:137], v[132:133], v[138:139], v[136:137]
	v_rcp_f32_e32 v147, v147
	v_mul_f32_e32 v132, 0xbfb8aa3b, v136
	v_exp_f32_e32 v132, v132
	v_mul_f32_e32 v133, 0xbfb8aa3b, v137
	v_exp_f32_e32 v133, v133
	v_pk_mul_f32 v[66:67], v[152:153], v[66:67]
	v_add_f32_e32 v132, 1.0, v132
	v_rcp_f32_e32 v144, v132
	v_add_f32_e32 v132, 1.0, v133
	v_rcp_f32_e32 v145, v132
	v_pk_mul_f32 v[132:133], v[142:143], v[146:147]
	v_lshlrev_b32_e32 v142, 16, v19
	v_and_b32_e32 v143, 0xffff0000, v19
	v_pk_fma_f32 v[130:131], v[130:131], v[142:143], 0 op_sel_hi:[1,1,0]
	v_lshlrev_b32_e32 v142, 16, v27
	v_and_b32_e32 v143, 0xffff0000, v27
	v_pk_fma_f32 v[126:127], v[126:127], v[142:143], v[130:131]
	v_lshlrev_b32_e32 v130, 16, v35
	v_and_b32_e32 v131, 0xffff0000, v35
	v_pk_fma_f32 v[122:123], v[122:123], v[130:131], v[126:127]
	v_lshlrev_b32_e32 v126, 16, v43
	v_and_b32_e32 v127, 0xffff0000, v43
	v_pk_fma_f32 v[118:119], v[118:119], v[126:127], v[122:123]
	v_lshlrev_b32_e32 v126, 16, v18
	v_and_b32_e32 v127, 0xffff0000, v18
	v_pk_fma_f32 v[126:127], v[128:129], v[126:127], 0 op_sel_hi:[1,1,0]
	v_lshlrev_b32_e32 v128, 16, v26
	v_and_b32_e32 v129, 0xffff0000, v26
	v_pk_fma_f32 v[124:125], v[124:125], v[128:129], v[126:127]
	v_lshlrev_b32_e32 v126, 16, v34
	v_and_b32_e32 v127, 0xffff0000, v34
	v_pk_fma_f32 v[120:121], v[120:121], v[126:127], v[124:125]
	v_lshlrev_b32_e32 v124, 16, v42
	v_and_b32_e32 v125, 0xffff0000, v42
	v_pk_fma_f32 v[116:117], v[116:117], v[124:125], v[120:121]
	v_lshlrev_b32_e32 v124, 16, v17
	v_and_b32_e32 v125, 0xffff0000, v17
	v_pk_fma_f32 v[14:15], v[14:15], v[124:125], 0 op_sel_hi:[1,1,0]
	v_lshlrev_b32_e32 v124, 16, v25
	v_and_b32_e32 v125, 0xffff0000, v25
	v_pk_fma_f32 v[10:11], v[10:11], v[124:125], v[14:15]
	v_lshlrev_b32_e32 v14, 16, v33
	v_and_b32_e32 v15, 0xffff0000, v33
	v_lshlrev_b32_e32 v152, 16, v22
	v_and_b32_e32 v153, 0xffff0000, v22
	v_pk_fma_f32 v[6:7], v[6:7], v[14:15], v[10:11]
	v_lshlrev_b32_e32 v10, 16, v41
	v_and_b32_e32 v11, 0xffff0000, v41
	v_pk_fma_f32 v[150:151], v[150:151], v[152:153], 0 op_sel_hi:[1,1,0]
	v_lshlrev_b32_e32 v152, 16, v30
	v_and_b32_e32 v153, 0xffff0000, v30
	v_pk_fma_f32 v[2:3], v[2:3], v[10:11], v[6:7]
	v_lshlrev_b32_e32 v10, 16, v16
	v_and_b32_e32 v11, 0xffff0000, v16
	v_pk_fma_f32 v[150:151], v[154:155], v[152:153], v[150:151]
	v_lshlrev_b32_e32 v152, 16, v38
	v_and_b32_e32 v153, 0xffff0000, v38
	v_pk_fma_f32 v[10:11], v[12:13], v[10:11], 0 op_sel_hi:[1,1,0]
	v_lshlrev_b32_e32 v12, 16, v24
	v_and_b32_e32 v13, 0xffff0000, v24
	v_pk_fma_f32 v[150:151], v[158:159], v[152:153], v[150:151]
	v_lshlrev_b32_e32 v152, 16, v46
	v_and_b32_e32 v153, 0xffff0000, v46
; #define LAS __attribute__((address_space(3)))
; DI V8 v8_from_bf(u32x4 w) { V8 r; r.a = (f32x4){bflo(w.x), bfhi(w.x), bflo(w.y), bfhi(w.y)}; r.b = (f32x4){bflo(w.z), bfhi(w.z), bflo(w.w), bfhi(w.w)}; return r; }
; DI float silu_f(float y) { return y * __builtin_amdgcn_rcpf(1.f + __builtin_amdgcn_exp2f(-1.4426950408889634f * y)); }
; DI void dn_intra(const Params& p, LAS unsigned char* L, int tid_in, int wave, int bid, int G, bool dry) {
;     ...
;         for (int part = 0; part < 3; ++part) {
;             float y[16];
; #pragma unroll
;             for (int e = 0; e < 16; ++e) y[e] = 0.f;
; #pragma unroll
;             for (int j = 0; j < 4; ++j) {
;                 const V8 x0 = v8_from_bf(xr[part][j][0]), x1 = v8_from_bf(xr[part][j][1]);
;                 const LAS float* wq = CW + j * 384 + part * 128 + sub * 16;
;                 const f32x4 wa = *(const LAS f32x4*)wq, wb = *(const LAS f32x4*)(wq + 4), wc = *(const LAS f32x4*)(wq + 8), wd = *(const LAS f32x4*)(wq + 12);
; #pragma unroll
;                 for (int e = 0; e < 4; ++e) { y[e] += wa[e] * x0.a[e]; y[4 + e] += wb[e] * x0.b[e]; y[8 + e] += wc[e] * x1.a[e]; y[12 + e] += wd[e] * x1.b[e]; }
;             }
;             float ss = 0.f;
; #pragma unroll
;             for (int e = 0; e < 16; ++e) { y[e] = silu_f(y[e]); ss += y[e] * y[e]; }
;             if (part < 2) { ss += __shfl_xor(ss, 1); ss += __shfl_xor(ss, 2); ss += __shfl_xor(ss, 4); }
	v_pk_fma_f32 v[8:9], v[8:9], v[12:13], v[10:11]
	v_lshlrev_b32_e32 v10, 16, v32
	v_and_b32_e32 v11, 0xffff0000, v32
	v_pk_fma_f32 v[152:153], v[162:163], v[152:153], v[150:151]
	v_pk_fma_f32 v[4:5], v[4:5], v[10:11], v[8:9]
	v_lshlrev_b32_e32 v8, 16, v40
	v_and_b32_e32 v9, 0xffff0000, v40
	v_mul_f32_e32 v150, 0xbfb8aa3b, v152
	v_pk_fma_f32 v[0:1], v[0:1], v[8:9], v[4:5]
	v_exp_f32_e32 v154, v150
	v_mul_f32_e32 v150, 0xbfb8aa3b, v153
	v_mul_f32_e32 v122, 0xbfb8aa3b, v118
	v_mul_f32_e32 v123, 0xbfb8aa3b, v119
	v_mul_f32_e32 v120, 0xbfb8aa3b, v116
	v_mul_f32_e32 v121, 0xbfb8aa3b, v117
	v_mul_f32_e32 v6, 0xbfb8aa3b, v2
	v_mul_f32_e32 v7, 0xbfb8aa3b, v3
	v_mul_f32_e32 v4, 0xbfb8aa3b, v0
	v_mul_f32_e32 v5, 0xbfb8aa3b, v1
	v_exp_f32_e32 v155, v150
	v_exp_f32_e32 v122, v122
	v_exp_f32_e32 v123, v123
	v_exp_f32_e32 v120, v120
	v_exp_f32_e32 v121, v121
	v_exp_f32_e32 v6, v6
	v_exp_f32_e32 v7, v7
	v_exp_f32_e32 v4, v4
	v_exp_f32_e32 v5, v5
	v_add_f32_e32 v154, 1.0, v154
	v_add_f32_e32 v155, 1.0, v155
	v_add_f32_e32 v122, 1.0, v122
	v_add_f32_e32 v123, 1.0, v123
	v_add_f32_e32 v120, 1.0, v120
	v_add_f32_e32 v121, 1.0, v121
	v_add_f32_e32 v6, 1.0, v6
	v_add_f32_e32 v7, 1.0, v7
	v_add_f32_e32 v4, 1.0, v4
	v_add_f32_e32 v5, 1.0, v5
	v_rcp_f32_e32 v154, v154
	v_rcp_f32_e32 v155, v155
	v_rcp_f32_e32 v122, v122
	v_rcp_f32_e32 v123, v123
	v_rcp_f32_e32 v120, v120
	v_rcp_f32_e32 v121, v121
	v_rcp_f32_e32 v6, v6
	v_rcp_f32_e32 v7, v7
	v_rcp_f32_e32 v4, v4
	v_rcp_f32_e32 v5, v5
	v_pk_mul_f32 v[134:135], v[152:153], v[154:155]
	v_pk_mul_f32 v[136:137], v[136:137], v[144:145]
	v_pk_mul_f32 v[144:145], v[118:119], v[122:123]
	v_pk_mul_f32 v[146:147], v[116:117], v[120:121]
	v_pk_mul_f32 v[152:153], v[2:3], v[6:7]
	v_pk_mul_f32 v[154:155], v[0:1], v[4:5]
	ds_read_b128 v[0:3], v182 offset:512
	ds_read_b128 v[116:119], v182 offset:528
	ds_read_b128 v[160:163], v182 offset:544
	ds_read_b128 v[156:159], v182 offset:560
	ds_read_b128 v[164:167], v182 offset:2080
	ds_read_b128 v[172:175], v182 offset:2096
	ds_read_b128 v[176:179], v182 offset:3616
	ds_read_b128 v[190:193], v182 offset:3632
	ds_read_b128 v[194:197], v182 offset:5152
	ds_read_b128 v[198:201], v182 offset:5168
	v_lshlrev_b32_e32 v4, 16, v55
	v_and_b32_e32 v5, 0xffff0000, v55
	s_waitcnt lgkmcnt(6)
	v_pk_fma_f32 v[4:5], v[158:159], v[4:5], 0 op_sel_hi:[1,1,0]
	v_lshlrev_b32_e32 v6, 16, v63
	v_and_b32_e32 v7, 0xffff0000, v63
	s_waitcnt lgkmcnt(4)
	v_pk_fma_f32 v[4:5], v[174:175], v[6:7], v[4:5]
	v_lshlrev_b32_e32 v6, 16, v75
	v_and_b32_e32 v7, 0xffff0000, v75
	s_waitcnt lgkmcnt(2)
	v_pk_fma_f32 v[4:5], v[192:193], v[6:7], v[4:5]
	v_lshlrev_b32_e32 v6, 16, v83
	v_and_b32_e32 v7, 0xffff0000, v83
	s_waitcnt lgkmcnt(0)
	v_pk_fma_f32 v[158:159], v[200:201], v[6:7], v[4:5]
	v_pk_mul_f32 v[142:143], v[136:137], v[136:137]
	v_mul_f32_e32 v4, 0xbfb8aa3b, v158
	v_exp_f32_e32 v8, v4
	v_mul_f32_e32 v4, 0xbfb8aa3b, v159
	v_exp_f32_e32 v9, v4
	ds_read_b128 v[4:7], v182 offset:2048
	ds_read_b128 v[120:123], v182 offset:2064
	v_add_f32_e32 v8, 1.0, v8
	v_rcp_f32_e32 v174, v8
	v_add_f32_e32 v8, 1.0, v9
	v_rcp_f32_e32 v175, v8
	ds_read_b128 v[12:15], v182 offset:3584
	ds_read_b128 v[128:131], v182 offset:3600
	ds_read_b128 v[8:11], v182 offset:5120
	ds_read_b128 v[124:127], v182 offset:5136
	v_pk_mul_f32 v[140:141], v[132:133], v[132:133]
	v_pk_mul_f32 v[138:139], v[134:135], v[134:135]
	v_pk_mul_f32 v[180:181], v[158:159], v[174:175]
	v_lshlrev_b32_e32 v158, 16, v54
	v_and_b32_e32 v159, 0xffff0000, v54
	v_pk_fma_f32 v[156:157], v[156:157], v[158:159], 0 op_sel_hi:[1,1,0]
	v_lshlrev_b32_e32 v158, 16, v62
	v_and_b32_e32 v159, 0xffff0000, v62
	v_pk_fma_f32 v[156:157], v[172:173], v[158:159], v[156:157]
	v_lshlrev_b32_e32 v158, 16, v74
	v_and_b32_e32 v159, 0xffff0000, v74
	v_pk_fma_f32 v[156:157], v[190:191], v[158:159], v[156:157]
	v_lshlrev_b32_e32 v158, 16, v82
	v_and_b32_e32 v159, 0xffff0000, v82
	v_pk_fma_f32 v[158:159], v[198:199], v[158:159], v[156:157]
	v_lshlrev_b32_e32 v174, 16, v53
	v_mul_f32_e32 v156, 0xbfb8aa3b, v158
	v_exp_f32_e32 v171, v156
	v_mul_f32_e32 v156, 0xbfb8aa3b, v159
	v_exp_f32_e32 v173, v156
	v_and_b32_e32 v175, 0xffff0000, v53
	v_add_f32_e32 v171, 1.0, v171
	v_rcp_f32_e32 v172, v171
	v_add_f32_e32 v171, 1.0, v173
	v_rcp_f32_e32 v173, v171
	v_pk_fma_f32 v[162:163], v[162:163], v[174:175], 0 op_sel_hi:[1,1,0]
	v_lshlrev_b32_e32 v174, 16, v61
	v_and_b32_e32 v175, 0xffff0000, v61
	v_pk_mul_f32 v[158:159], v[158:159], v[172:173]
	v_lshlrev_b32_e32 v172, 16, v52
	v_and_b32_e32 v173, 0xffff0000, v52
	v_pk_fma_f32 v[160:161], v[160:161], v[172:173], 0 op_sel_hi:[1,1,0]
	v_lshlrev_b32_e32 v172, 16, v60
	v_and_b32_e32 v173, 0xffff0000, v60
	v_pk_fma_f32 v[160:161], v[164:165], v[172:173], v[160:161]
	v_lshlrev_b32_e32 v164, 16, v72
	v_and_b32_e32 v165, 0xffff0000, v72
	v_pk_fma_f32 v[160:161], v[176:177], v[164:165], v[160:161]
	v_lshlrev_b32_e32 v164, 16, v80
	v_and_b32_e32 v165, 0xffff0000, v80
	v_pk_fma_f32 v[164:165], v[194:195], v[164:165], v[160:161]
	v_pk_fma_f32 v[162:163], v[166:167], v[174:175], v[162:163]
	v_mul_f32_e32 v160, 0xbfb8aa3b, v164
	v_exp_f32_e32 v160, v160
	v_mul_f32_e32 v161, 0xbfb8aa3b, v165
	v_exp_f32_e32 v161, v161
	v_lshlrev_b32_e32 v166, 16, v73
	v_add_f32_e32 v160, 1.0, v160
	v_rcp_f32_e32 v172, v160
	v_add_f32_e32 v160, 1.0, v161
	v_rcp_f32_e32 v173, v160
	v_and_b32_e32 v167, 0xffff0000, v73
	v_pk_fma_f32 v[162:163], v[178:179], v[166:167], v[162:163]
	v_lshlrev_b32_e32 v166, 16, v81
	v_pk_mul_f32 v[164:165], v[164:165], v[172:173]
	v_lshlrev_b32_e32 v172, 16, v51
	v_and_b32_e32 v173, 0xffff0000, v51
	v_pk_fma_f32 v[118:119], v[118:119], v[172:173], 0 op_sel_hi:[1,1,0]
	v_lshlrev_b32_e32 v172, 16, v59
	v_and_b32_e32 v173, 0xffff0000, v59
	s_waitcnt lgkmcnt(4)
; #define LAS __attribute__((address_space(3)))
; DI V8 v8_from_bf(u32x4 w) { V8 r; r.a = (f32x4){bflo(w.x), bfhi(w.x), bflo(w.y), bfhi(w.y)}; r.b = (f32x4){bflo(w.z), bfhi(w.z), bflo(w.w), bfhi(w.w)}; return r; }
; DI float silu_f(float y) { return y * __builtin_amdgcn_rcpf(1.f + __builtin_amdgcn_exp2f(-1.4426950408889634f * y)); }
; DI void dn_intra(const Params& p, LAS unsigned char* L, int tid_in, int wave, int bid, int G, bool dry) {
;     ...
;         for (int part = 0; part < 3; ++part) {
;             float y[16];
; #pragma unroll
;             for (int e = 0; e < 16; ++e) y[e] = 0.f;
; #pragma unroll
;             for (int j = 0; j < 4; ++j) {
;                 const V8 x0 = v8_from_bf(xr[part][j][0]), x1 = v8_from_bf(xr[part][j][1]);
;                 const LAS float* wq = CW + j * 384 + part * 128 + sub * 16;
;                 const f32x4 wa = *(const LAS f32x4*)wq, wb = *(const LAS f32x4*)(wq + 4), wc = *(const LAS f32x4*)(wq + 8), wd = *(const LAS f32x4*)(wq + 12);
; #pragma unroll
;                 for (int e = 0; e < 4; ++e) { y[e] += wa[e] * x0.a[e]; y[4 + e] += wb[e] * x0.b[e]; y[8 + e] += wc[e] * x1.a[e]; y[12 + e] += wd[e] * x1.b[e]; }
;             }
;             float ss = 0.f;
; #pragma unroll
;             for (int e = 0; e < 16; ++e) { y[e] = silu_f(y[e]); ss += y[e] * y[e]; }
;             if (part < 2) { ss += __shfl_xor(ss, 1); ss += __shfl_xor(ss, 2); ss += __shfl_xor(ss, 4); }
	v_pk_fma_f32 v[118:119], v[122:123], v[172:173], v[118:119]
	v_lshlrev_b32_e32 v122, 16, v71
	v_and_b32_e32 v123, 0xffff0000, v71
	s_waitcnt lgkmcnt(2)
	v_pk_fma_f32 v[118:119], v[130:131], v[122:123], v[118:119]
	v_lshlrev_b32_e32 v130, 16, v50
	v_and_b32_e32 v131, 0xffff0000, v50
	v_pk_fma_f32 v[116:117], v[116:117], v[130:131], 0 op_sel_hi:[1,1,0]
	v_lshlrev_b32_e32 v130, 16, v58
	v_and_b32_e32 v131, 0xffff0000, v58
	v_pk_fma_f32 v[116:117], v[120:121], v[130:131], v[116:117]
	v_lshlrev_b32_e32 v120, 16, v70
	v_and_b32_e32 v121, 0xffff0000, v70
	v_pk_fma_f32 v[116:117], v[128:129], v[120:121], v[116:117]
	v_lshlrev_b32_e32 v120, 16, v78
	v_and_b32_e32 v121, 0xffff0000, v78
	s_waitcnt lgkmcnt(0)
	v_pk_fma_f32 v[116:117], v[124:125], v[120:121], v[116:117]
	v_lshlrev_b32_e32 v124, 16, v49
	v_and_b32_e32 v125, 0xffff0000, v49
	v_pk_fma_f32 v[2:3], v[2:3], v[124:125], 0 op_sel_hi:[1,1,0]
	v_lshlrev_b32_e32 v124, 16, v57
	v_and_b32_e32 v125, 0xffff0000, v57
	v_pk_fma_f32 v[2:3], v[6:7], v[124:125], v[2:3]
	v_lshlrev_b32_e32 v6, 16, v69
	v_and_b32_e32 v7, 0xffff0000, v69
	v_pk_fma_f32 v[2:3], v[14:15], v[6:7], v[2:3]
	v_lshlrev_b32_e32 v6, 16, v77
	v_and_b32_e32 v7, 0xffff0000, v77
	v_pk_fma_f32 v[2:3], v[10:11], v[6:7], v[2:3]
	v_lshlrev_b32_e32 v10, 16, v48
	v_and_b32_e32 v11, 0xffff0000, v48
	v_pk_fma_f32 v[0:1], v[0:1], v[10:11], 0 op_sel_hi:[1,1,0]
	v_lshlrev_b32_e32 v10, 16, v56
	v_and_b32_e32 v11, 0xffff0000, v56
	v_pk_fma_f32 v[0:1], v[4:5], v[10:11], v[0:1]
	v_lshlrev_b32_e32 v4, 16, v68
	v_and_b32_e32 v5, 0xffff0000, v68
	v_pk_fma_f32 v[0:1], v[12:13], v[4:5], v[0:1]
	v_lshlrev_b32_e32 v4, 16, v76
	v_and_b32_e32 v5, 0xffff0000, v76
	v_pk_fma_f32 v[0:1], v[8:9], v[4:5], v[0:1]
	v_lshlrev_b32_e32 v122, 16, v79
	v_mul_f32_e32 v4, 0xbfb8aa3b, v0
	v_mul_f32_e32 v5, 0xbfb8aa3b, v1
	v_and_b32_e32 v123, 0xffff0000, v79
	v_exp_f32_e32 v4, v4
	v_exp_f32_e32 v5, v5
	v_pk_fma_f32 v[118:119], v[126:127], v[122:123], v[118:119]
	v_mul_f32_e32 v120, 0xbfb8aa3b, v116
	v_mul_f32_e32 v121, 0xbfb8aa3b, v117
	v_mul_f32_e32 v6, 0xbfb8aa3b, v2
	v_mul_f32_e32 v7, 0xbfb8aa3b, v3
	v_mul_f32_e32 v122, 0xbfb8aa3b, v118
	v_exp_f32_e32 v120, v120
	v_exp_f32_e32 v121, v121
	v_exp_f32_e32 v6, v6
	v_exp_f32_e32 v7, v7
	v_exp_f32_e32 v126, v122
	v_mul_f32_e32 v122, 0xbfb8aa3b, v119
	v_exp_f32_e32 v127, v122
	v_add_f32_e32 v4, 1.0, v4
	v_add_f32_e32 v5, 1.0, v5
	v_rcp_f32_e32 v4, v4
	v_rcp_f32_e32 v5, v5
	v_and_b32_e32 v167, 0xffff0000, v81
	v_add_f32_e32 v120, 1.0, v120
	v_add_f32_e32 v121, 1.0, v121
	v_add_f32_e32 v6, 1.0, v6
	v_add_f32_e32 v7, 1.0, v7
	v_pk_fma_f32 v[162:163], v[196:197], v[166:167], v[162:163]
	v_rcp_f32_e32 v120, v120
	v_rcp_f32_e32 v121, v121
	v_rcp_f32_e32 v6, v6
	v_rcp_f32_e32 v7, v7
	v_mul_f32_e32 v166, 0xbfb8aa3b, v162
	v_mul_f32_e32 v167, 0xbfb8aa3b, v163
	v_add_f32_e32 v126, 1.0, v126
	v_add_f32_e32 v127, 1.0, v127
	v_exp_f32_e32 v166, v166
	v_exp_f32_e32 v167, v167
	v_rcp_f32_e32 v126, v126
	v_rcp_f32_e32 v127, v127
	v_pk_mul_f32 v[0:1], v[0:1], v[4:5]
	v_mov_b32_e32 v125, v155
	v_mov_b32_e32 v124, v1
	v_pk_mul_f32 v[10:11], v[116:117], v[120:121]
	v_pk_mul_f32 v[2:3], v[2:3], v[6:7]
	v_mov_b32_e32 v120, v0
	v_mov_b32_e32 v121, v154
	v_pk_mul_f32 v[124:125], v[124:125], v[124:125]
	v_mov_b32_e32 v116, v2
	v_mov_b32_e32 v117, v152
	v_pk_fma_f32 v[120:121], v[120:121], v[120:121], v[124:125]
	v_add_f32_e32 v166, 1.0, v166
	v_add_f32_e32 v167, 1.0, v167
	v_pk_mul_f32 v[8:9], v[118:119], v[126:127]
	v_mov_b32_e32 v118, v3
	v_mov_b32_e32 v119, v153
	v_pk_fma_f32 v[116:117], v[116:117], v[116:117], v[120:121]
	v_rcp_f32_e32 v166, v166
	v_rcp_f32_e32 v167, v167
	v_mov_b32_e32 v12, v10
	v_mov_b32_e32 v13, v146
	v_pk_fma_f32 v[116:117], v[118:119], v[118:119], v[116:117]
	v_mov_b32_e32 v14, v11
	v_mov_b32_e32 v15, v147
	v_pk_fma_f32 v[12:13], v[12:13], v[12:13], v[116:117]
	v_mov_b32_e32 v4, v8
	v_mov_b32_e32 v5, v144
	v_pk_fma_f32 v[12:13], v[14:15], v[14:15], v[12:13]
	v_pk_mul_f32 v[122:123], v[164:165], v[164:165]
	v_mov_b32_e32 v6, v9
	v_mov_b32_e32 v7, v145
	v_pk_fma_f32 v[4:5], v[4:5], v[4:5], v[12:13]
	v_pk_mul_f32 v[162:163], v[162:163], v[166:167]
	v_pk_fma_f32 v[4:5], v[6:7], v[6:7], v[4:5]
	v_mov_b32_e32 v6, v122
	v_mov_b32_e32 v7, v142
	v_pk_mul_f32 v[166:167], v[162:163], v[162:163]
	v_pk_add_f32 v[4:5], v[6:7], v[4:5]
	v_mov_b32_e32 v142, v123
	v_pk_add_f32 v[4:5], v[142:143], v[4:5]
	v_mov_b32_e32 v6, v166
	v_mov_b32_e32 v7, v140
	v_pk_mul_f32 v[160:161], v[158:159], v[158:159]
	v_pk_add_f32 v[4:5], v[6:7], v[4:5]
	v_mov_b32_e32 v140, v167
	v_pk_add_f32 v[4:5], v[140:141], v[4:5]
	v_mov_b32_e32 v6, v160
	v_mov_b32_e32 v7, v138
	v_pk_mul_f32 v[150:151], v[66:67], v[66:67]
	v_pk_mul_f32 v[156:157], v[180:181], v[180:181]
	v_pk_add_f32 v[4:5], v[6:7], v[4:5]
	v_mov_b32_e32 v138, v161
	v_pk_add_f32 v[4:5], v[138:139], v[4:5]
	v_mov_b32_e32 v6, v156
	v_mov_b32_e32 v7, v150
	v_pk_add_f32 v[4:5], v[6:7], v[4:5]
	v_mov_b32_e32 v150, v157
	v_pk_add_f32 v[4:5], v[150:151], v[4:5]
	ds_bpermute_b32 v7, v170, v5
	ds_bpermute_b32 v6, v170, v4
	v_xor_b32_e32 v12, 2, v168
	v_cmp_lt_i32_e32 vcc, v12, v169
	s_mov_b32 s0, 0x358637bd
	v_ashrrev_i32_e32 v189, 3, v187
	v_cndmask_b32_e32 v12, v168, v12, vcc
	v_lshlrev_b32_e32 v12, 2, v12
	s_waitcnt lgkmcnt(0)
	v_pk_add_f32 v[4:5], v[4:5], v[6:7]
	ds_bpermute_b32 v7, v12, v5
	ds_bpermute_b32 v6, v12, v4
	v_xor_b32_e32 v12, 4, v168
	v_cmp_lt_i32_e32 vcc, v12, v169
	v_mov_b32_e32 v184, s90
	v_lshlrev_b32_e32 v64, 5, v64
	v_cndmask_b32_e32 v12, v168, v12, vcc
	v_lshlrev_b32_e32 v12, 2, v12
	s_waitcnt lgkmcnt(0)
; #define LAS __attribute__((address_space(3)))
; DI unsigned pk2(float lo, float hi) { f32x2 v = {lo, hi}; bf16x2_t b = __builtin_convertvector(v, bf16x2_t); return __builtin_bit_cast(unsigned, b); }
; DI float silu_f(float y) { return y * __builtin_amdgcn_rcpf(1.f + __builtin_amdgcn_exp2f(-1.4426950408889634f * y)); }
; DI void dn_intra(const Params& p, LAS unsigned char* L, int tid_in, int wave, int bid, int G, bool dry) {
;     ...
;             float ss = 0.f;
; #pragma unroll
;             for (int e = 0; e < 16; ++e) { y[e] = silu_f(y[e]); ss += y[e] * y[e]; }
;             if (part < 2) { ss += __shfl_xor(ss, 1); ss += __shfl_xor(ss, 2); ss += __shfl_xor(ss, 4); }
;             if (part == 0) { rq = rsqrtf(ss + EPS) * 0.08838834764831845f;
; #pragma unroll
;                 for (int e = 0; e < 16; ++e) qv[e] = y[e] * rq; }
;             else if (part == 1) { rk = rsqrtf(ss + EPS);
; #pragma unroll
;                 for (int e = 0; e < 16; ++e) kv[e] = y[e] * rk; }
;             else {
; #pragma unroll
;                 for (int e = 0; e < 16; ++e) vv[e] = y[e]; }
;         }
;         lds_barrier();
;         const float beta = betas[r], gcr = gcs[r], gl = gcs[63];
;         { u32x4 w0, w1; w0.x = pk2(qv[0], qv[1]); w0.y = pk2(qv[2], qv[3]); w0.z = pk2(qv[4], qv[5]); w0.w = pk2(qv[6], qv[7]); w1.x = pk2(qv[8], qv[9]); w1.y = pk2(qv[10], qv[11]); w1.z = pk2(qv[12], qv[13]); w1.w = pk2(qv[14], qv[15]);
;           *(LAS u32x4*)(L + DN_QS + r * 272 + sub * 32) = w0; *(LAS u32x4*)(L + DN_QS + r * 272 + sub * 32 + 16) = w1;
;           w0.x = pk2(kv[0], kv[1]); w0.y = pk2(kv[2], kv[3]); w0.z = pk2(kv[4], kv[5]); w0.w = pk2(kv[6], kv[7]); w1.x = pk2(kv[8], kv[9]); w1.y = pk2(kv[10], kv[11]); w1.z = pk2(kv[12], kv[13]); w1.w = pk2(kv[14], kv[15]);
;           *(LAS u32x4*)(L + DN_KS + r * 272 + sub * 32) = w0; *(LAS u32x4*)(L + DN_KS + r * 272 + sub * 32 + 16) = w1;
;           w0.x = pk2(kv[0] * beta, kv[1] * beta); w0.y = pk2(kv[2] * beta, kv[3] * beta); w0.z = pk2(kv[4] * beta, kv[5] * beta); w0.w = pk2(kv[6] * beta, kv[7] * beta);
;           w1.x = pk2(kv[8] * beta, kv[9] * beta); w1.y = pk2(kv[10] * beta, kv[11] * beta); w1.z = pk2(kv[12] * beta, kv[13] * beta); w1.w = pk2(kv[14] * beta, kv[15] * beta);
;           *(LAS u32x4*)(L + DN_KBS + r * 272 + sub * 32) = w0; *(LAS u32x4*)(L + DN_KBS + r * 272 + sub * 32 + 16) = w1;
	v_pk_add_f32 v[4:5], v[4:5], v[6:7]
	ds_bpermute_b32 v7, v12, v5
	ds_bpermute_b32 v6, v12, v4
	v_mul_lo_u32 v191, v189, s91
	v_add3_u32 v188, s85, v191, v188
	s_waitcnt lgkmcnt(0)
	v_pk_add_f32 v[4:5], v[4:5], v[6:7]
	s_nop 0
	v_pk_add_f32 v[4:5], v[4:5], s[0:1] op_sel_hi:[1,0]
	s_lshl_b32 s0, s13, 3
	v_mul_f32_e32 v6, 0x4b800000, v5
	v_cmp_gt_f32_e32 vcc, s87, v5
	s_or_b32 s0, s0, s12
	s_nop 0
	v_cndmask_b32_e32 v5, v5, v6, vcc
	v_rsq_f32_e32 v5, v5
	s_nop 0
	v_mul_f32_e32 v6, 0x45800000, v5
	v_cndmask_b32_e32 v5, v5, v6, vcc
	v_mul_f32_e32 v6, 0x3db504f3, v5
	v_mul_f32_e32 v5, 0x4b800000, v4
	v_cmp_gt_f32_e32 vcc, s87, v4
	v_pk_mul_f32 v[174:175], v[66:67], v[6:7] op_sel_hi:[1,0]
	v_pk_mul_f32 v[160:161], v[154:155], v[6:7] op_sel_hi:[1,0]
	v_cndmask_b32_e32 v4, v4, v5, vcc
	v_rsq_f32_e32 v4, v4
	v_pk_mul_f32 v[156:157], v[152:153], v[6:7] op_sel_hi:[1,0]
	v_pk_mul_f32 v[154:155], v[146:147], v[6:7] op_sel_hi:[1,0]
	v_pk_mul_f32 v[152:153], v[144:145], v[6:7] op_sel_hi:[1,0]
	v_mul_f32_e32 v5, 0x45800000, v4
	v_cndmask_b32_e32 v4, v4, v5, vcc
	v_pk_mul_f32 v[66:67], v[180:181], v[4:5] op_sel_hi:[1,0]
	v_lshl_add_u32 v180, v189, 2, 0
	v_pk_mul_f32 v[150:151], v[136:137], v[6:7] op_sel_hi:[1,0]
	v_pk_mul_f32 v[178:179], v[132:133], v[6:7] op_sel_hi:[1,0]
	v_pk_mul_f32 v[176:177], v[134:135], v[6:7] op_sel_hi:[1,0]
	v_pk_mul_f32 v[172:173], v[0:1], v[4:5] op_sel_hi:[1,0]
	v_pk_mul_f32 v[170:171], v[2:3], v[4:5] op_sel_hi:[1,0]
	v_pk_mul_f32 v[168:169], v[10:11], v[4:5] op_sel_hi:[1,0]
	v_pk_mul_f32 v[166:167], v[8:9], v[4:5] op_sel_hi:[1,0]
	v_pk_mul_f32 v[164:165], v[164:165], v[4:5] op_sel_hi:[1,0]
	v_pk_mul_f32 v[162:163], v[162:163], v[4:5] op_sel_hi:[1,0]
	v_pk_mul_f32 v[158:159], v[158:159], v[4:5] op_sel_hi:[1,0]
	ds_read_b128 v[192:195], v182 offset:1024
	ds_read_b128 v[144:147], v182 offset:1040
	ds_read_b128 v[128:131], v182 offset:1056
	ds_read_b128 v[12:15], v182 offset:1072
	ds_read_b128 v[196:199], v182 offset:2560
	ds_read_b128 v[140:143], v182 offset:2576
	ds_read_b128 v[124:127], v182 offset:2592
	ds_read_b128 v[8:11], v182 offset:2608
	ds_read_b128 v[200:203], v182 offset:4096
	ds_read_b128 v[136:139], v182 offset:4112
	ds_read_b128 v[120:123], v182 offset:4128
	ds_read_b128 v[4:7], v182 offset:4144
	ds_read_b128 v[204:207], v182 offset:5632
	ds_read_b128 v[132:135], v182 offset:5648
	ds_read_b128 v[116:119], v182 offset:5664
	ds_read_b128 v[0:3], v182 offset:5680
	s_waitcnt lgkmcnt(0)
	s_barrier
	v_add_u32_e32 v181, 0x21500, v180
	v_add_u32_e32 v182, 0x21400, v180
	ds_read_b32 v180, v181
	ds_read_b32 v190, v182
	ds_read_b32 v181, v184
	v_mul_lo_u32 v182, v189, s84
	v_cvt_pk_bf16_f32 v208, v160, v161
	v_cvt_pk_bf16_f32 v209, v156, v157
	v_cvt_pk_bf16_f32 v210, v154, v155
	v_cvt_pk_bf16_f32 v211, v152, v153
	v_add3_u32 v184, 0, v182, v64
	v_cvt_pk_bf16_f32 v212, v150, v151
	v_cvt_pk_bf16_f32 v213, v178, v179
	v_cvt_pk_bf16_f32 v214, v176, v177
	v_cvt_pk_bf16_f32 v215, v174, v175
	ds_write_b128 v184, v[208:211] offset:17408
	ds_write_b128 v184, v[212:215] offset:17424
	v_cvt_pk_bf16_f32 v208, v172, v173
	v_cvt_pk_bf16_f32 v209, v170, v171
	v_cvt_pk_bf16_f32 v210, v168, v169
	v_cvt_pk_bf16_f32 v211, v166, v167
	v_cvt_pk_bf16_f32 v212, v164, v165
	v_cvt_pk_bf16_f32 v213, v162, v163
	v_cvt_pk_bf16_f32 v214, v158, v159
	v_cvt_pk_bf16_f32 v215, v66, v67
	ds_write_b128 v184, v[208:211] offset:34816
	ds_write_b128 v184, v[212:215] offset:34832
	s_waitcnt lgkmcnt(4)
	v_pk_mul_f32 v[208:209], v[180:181], v[172:173] op_sel_hi:[0,1]
	v_pk_mul_f32 v[210:211], v[180:181], v[170:171] op_sel_hi:[0,1]
	v_cvt_pk_bf16_f32 v208, v208, v209
	v_cvt_pk_bf16_f32 v209, v210, v211
	v_pk_mul_f32 v[210:211], v[180:181], v[168:169] op_sel_hi:[0,1]
	v_pk_mul_f32 v[212:213], v[180:181], v[166:167] op_sel_hi:[0,1]
	v_cvt_pk_bf16_f32 v210, v210, v211
	v_cvt_pk_bf16_f32 v211, v212, v213
	v_pk_mul_f32 v[212:213], v[180:181], v[164:165] op_sel_hi:[0,1]
	v_pk_mul_f32 v[214:215], v[180:181], v[162:163] op_sel_hi:[0,1]
	v_cvt_pk_bf16_f32 v212, v212, v213
	v_cvt_pk_bf16_f32 v213, v214, v215
	v_pk_mul_f32 v[214:215], v[180:181], v[158:159] op_sel_hi:[0,1]
	v_pk_mul_f32 v[218:219], v[180:181], v[66:67] op_sel_hi:[0,1]
	v_cvt_pk_bf16_f32 v214, v214, v215
	v_cvt_pk_bf16_f32 v215, v218, v219
	ds_write_b128 v184, v[208:211] offset:52224
	ds_write_b128 v184, v[212:215] offset:52240
	v_lshlrev_b32_e32 v208, 16, v84
	v_and_b32_e32 v209, 0xffff0000, v84
	v_pk_fma_f32 v[192:193], v[192:193], v[208:209], 0 op_sel_hi:[1,1,0]
	v_lshlrev_b32_e32 v208, 16, v92
	v_and_b32_e32 v209, 0xffff0000, v92
	v_pk_fma_f32 v[192:193], v[196:197], v[208:209], v[192:193]
	v_lshlrev_b32_e32 v196, 16, v100
	v_and_b32_e32 v197, 0xffff0000, v100
	v_pk_fma_f32 v[192:193], v[200:201], v[196:197], v[192:193]
	v_lshlrev_b32_e32 v196, 16, v108
	v_and_b32_e32 v197, 0xffff0000, v108
	v_pk_fma_f32 v[192:193], v[204:205], v[196:197], v[192:193]
	v_lshlrev_b32_e32 v204, 16, v85
	v_and_b32_e32 v205, 0xffff0000, v85
	v_pk_fma_f32 v[194:195], v[194:195], v[204:205], 0 op_sel_hi:[1,1,0]
	v_lshlrev_b32_e32 v204, 16, v93
	v_and_b32_e32 v205, 0xffff0000, v93
	v_pk_fma_f32 v[194:195], v[198:199], v[204:205], v[194:195]
	v_lshlrev_b32_e32 v198, 16, v101
	v_and_b32_e32 v199, 0xffff0000, v101
	v_mul_f32_e32 v191, 0xbfb8aa3b, v192
	v_pk_fma_f32 v[194:195], v[202:203], v[198:199], v[194:195]
	v_lshlrev_b32_e32 v198, 16, v109
	v_and_b32_e32 v199, 0xffff0000, v109
	v_exp_f32_e32 v191, v191
	v_mul_f32_e32 v196, 0xbfb8aa3b, v193
	v_pk_fma_f32 v[198:199], v[206:207], v[198:199], v[194:195]
	v_exp_f32_e32 v201, v196
	v_mul_f32_e32 v194, 0xbfb8aa3b, v198
	v_exp_f32_e32 v194, v194
	v_mul_f32_e32 v195, 0xbfb8aa3b, v199
; #define LAS __attribute__((address_space(3)))
; DI unsigned pk2(float lo, float hi) { f32x2 v = {lo, hi}; bf16x2_t b = __builtin_convertvector(v, bf16x2_t); return __builtin_bit_cast(unsigned, b); }
; DI void dn_intra(const Params& p, LAS unsigned char* L, int tid_in, int wave, int bid, int G, bool dry) {
;     ...
;             else if (part == 1) { rk = rsqrtf(ss + EPS);
; #pragma unroll
;                 for (int e = 0; e < 16; ++e) kv[e] = y[e] * rk; }
;             else {
; #pragma unroll
;                 for (int e = 0; e < 16; ++e) vv[e] = y[e]; }
;         }
;         lds_barrier();
;         const float beta = betas[r], gcr = gcs[r], gl = gcs[63];
;         { u32x4 w0, w1; w0.x = pk2(qv[0], qv[1]); w0.y = pk2(qv[2], qv[3]); w0.z = pk2(qv[4], qv[5]); w0.w = pk2(qv[6], qv[7]); w1.x = pk2(qv[8], qv[9]); w1.y = pk2(qv[10], qv[11]); w1.z = pk2(qv[12], qv[13]); w1.w = pk2(qv[14], qv[15]);
;           *(LAS u32x4*)(L + DN_QS + r * 272 + sub * 32) = w0; *(LAS u32x4*)(L + DN_QS + r * 272 + sub * 32 + 16) = w1;
;           w0.x = pk2(kv[0], kv[1]); w0.y = pk2(kv[2], kv[3]); w0.z = pk2(kv[4], kv[5]); w0.w = pk2(kv[6], kv[7]); w1.x = pk2(kv[8], kv[9]); w1.y = pk2(kv[10], kv[11]); w1.z = pk2(kv[12], kv[13]); w1.w = pk2(kv[14], kv[15]);
;           *(LAS u32x4*)(L + DN_KS + r * 272 + sub * 32) = w0; *(LAS u32x4*)(L + DN_KS + r * 272 + sub * 32 + 16) = w1;
;           w0.x = pk2(kv[0] * beta, kv[1] * beta); w0.y = pk2(kv[2] * beta, kv[3] * beta); w0.z = pk2(kv[4] * beta, kv[5] * beta); w0.w = pk2(kv[6] * beta, kv[7] * beta);
;           w1.x = pk2(kv[8] * beta, kv[9] * beta); w1.y = pk2(kv[10] * beta, kv[11] * beta); w1.z = pk2(kv[12] * beta, kv[13] * beta); w1.w = pk2(kv[14] * beta, kv[15] * beta);
;           *(LAS u32x4*)(L + DN_KBS + r * 272 + sub * 32) = w0; *(LAS u32x4*)(L + DN_KBS + r * 272 + sub * 32 + 16) = w1;
;           const float kb = beta * __expf(gcr);
; #pragma unroll
;           for (int e4 = 0; e4 < 4; ++e4) { *(LAS f32x4*)(RHS + r * DN_RST + 128 + sub * 16 + e4 * 4) = (f32x4){kv[4 * e4] * kb, kv[4 * e4 + 1] * kb, kv[4 * e4 + 2] * kb, kv[4 * e4 + 3] * kb};
;               *(LAS f32x4*)(RHS + r * DN_RST + sub * 16 + e4 * 4) = (f32x4){vv[4 * e4] * beta, vv[4 * e4 + 1] * beta, vv[4 * e4 + 2] * beta, vv[4 * e4 + 3] * beta}; } }
	v_exp_f32_e32 v195, v195
	v_add_f32_e32 v191, 1.0, v191
	v_mul_f32_e32 v182, 0x3fb8aa3b, v190
	v_rcp_f32_e32 v200, v191
	v_add_f32_e32 v191, 1.0, v201
	v_exp_f32_e32 v182, v182
	v_rcp_f32_e32 v201, v191
	v_add_f32_e32 v191, 1.0, v194
	v_rcp_f32_e32 v202, v191
	v_add_f32_e32 v191, 1.0, v195
	v_rcp_f32_e32 v203, v191
	v_mul_f32_e32 v184, v180, v182
	v_pk_mul_f32 v[196:197], v[184:185], v[170:171] op_sel_hi:[0,1]
	v_pk_mul_f32 v[194:195], v[184:185], v[172:173] op_sel_hi:[0,1]
	ds_write_b128 v188, v[194:197] offset:512
	v_pk_mul_f32 v[192:193], v[192:193], v[200:201]
	v_pk_mul_f32 v[194:195], v[198:199], v[202:203]
	v_pk_mul_f32 v[192:193], v[180:181], v[192:193] op_sel_hi:[0,1]
	v_pk_mul_f32 v[194:195], v[180:181], v[194:195] op_sel_hi:[0,1]
	ds_write_b128 v188, v[192:195]
	v_lshlrev_b32_e32 v192, 16, v86
	v_and_b32_e32 v193, 0xffff0000, v86
	v_pk_fma_f32 v[144:145], v[144:145], v[192:193], 0 op_sel_hi:[1,1,0]
	v_lshlrev_b32_e32 v192, 16, v94
	v_and_b32_e32 v193, 0xffff0000, v94
	v_pk_fma_f32 v[140:141], v[140:141], v[192:193], v[144:145]
	v_lshlrev_b32_e32 v144, 16, v102
	v_and_b32_e32 v145, 0xffff0000, v102
	v_pk_fma_f32 v[136:137], v[136:137], v[144:145], v[140:141]
	v_lshlrev_b32_e32 v144, 16, v87
	v_and_b32_e32 v145, 0xffff0000, v87
	v_pk_fma_f32 v[144:145], v[146:147], v[144:145], 0 op_sel_hi:[1,1,0]
	v_lshlrev_b32_e32 v146, 16, v95
	v_and_b32_e32 v147, 0xffff0000, v95
	v_pk_fma_f32 v[142:143], v[142:143], v[146:147], v[144:145]
	v_lshlrev_b32_e32 v144, 16, v103
	v_and_b32_e32 v145, 0xffff0000, v103
	v_lshlrev_b32_e32 v140, 16, v110
	v_and_b32_e32 v141, 0xffff0000, v110
	v_pk_fma_f32 v[138:139], v[138:139], v[144:145], v[142:143]
	v_lshlrev_b32_e32 v142, 16, v111
	v_and_b32_e32 v143, 0xffff0000, v111
	v_pk_fma_f32 v[132:133], v[132:133], v[140:141], v[136:137]
	v_pk_fma_f32 v[138:139], v[134:135], v[142:143], v[138:139]
	v_mul_f32_e32 v136, 0xbfb8aa3b, v132
	v_mul_f32_e32 v134, 0xbfb8aa3b, v138
	v_exp_f32_e32 v140, v136
	v_mul_f32_e32 v136, 0xbfb8aa3b, v133
	v_exp_f32_e32 v134, v134
	v_mul_f32_e32 v135, 0xbfb8aa3b, v139
	v_exp_f32_e32 v141, v136
	v_exp_f32_e32 v135, v135
	v_add_f32_e32 v134, 1.0, v134
	v_add_f32_e32 v140, 1.0, v140
	v_add_f32_e32 v141, 1.0, v141
	v_rcp_f32_e32 v142, v134
	v_add_f32_e32 v134, 1.0, v135
	v_rcp_f32_e32 v140, v140
	v_rcp_f32_e32 v141, v141
	v_rcp_f32_e32 v143, v134
	v_pk_mul_f32 v[136:137], v[184:185], v[166:167] op_sel_hi:[0,1]
	v_pk_mul_f32 v[134:135], v[184:185], v[168:169] op_sel_hi:[0,1]
	ds_write_b128 v188, v[134:137] offset:528
	v_pk_mul_f32 v[132:133], v[132:133], v[140:141]
	v_pk_mul_f32 v[134:135], v[138:139], v[142:143]
	v_pk_mul_f32 v[132:133], v[180:181], v[132:133] op_sel_hi:[0,1]
	v_pk_mul_f32 v[134:135], v[180:181], v[134:135] op_sel_hi:[0,1]
	ds_write_b128 v188, v[132:135] offset:16
	v_lshlrev_b32_e32 v132, 16, v88
	v_and_b32_e32 v133, 0xffff0000, v88
	v_pk_fma_f32 v[128:129], v[128:129], v[132:133], 0 op_sel_hi:[1,1,0]
	v_lshlrev_b32_e32 v132, 16, v96
	v_and_b32_e32 v133, 0xffff0000, v96
	v_pk_fma_f32 v[124:125], v[124:125], v[132:133], v[128:129]
	v_lshlrev_b32_e32 v128, 16, v104
	v_and_b32_e32 v129, 0xffff0000, v104
	v_pk_fma_f32 v[120:121], v[120:121], v[128:129], v[124:125]
	v_lshlrev_b32_e32 v128, 16, v89
	v_and_b32_e32 v129, 0xffff0000, v89
	v_pk_fma_f32 v[128:129], v[130:131], v[128:129], 0 op_sel_hi:[1,1,0]
	v_lshlrev_b32_e32 v130, 16, v97
	v_and_b32_e32 v131, 0xffff0000, v97
	v_pk_fma_f32 v[126:127], v[126:127], v[130:131], v[128:129]
	v_lshlrev_b32_e32 v128, 16, v105
	v_and_b32_e32 v129, 0xffff0000, v105
	v_lshlrev_b32_e32 v124, 16, v112
	v_and_b32_e32 v125, 0xffff0000, v112
	v_pk_fma_f32 v[122:123], v[122:123], v[128:129], v[126:127]
	v_lshlrev_b32_e32 v126, 16, v113
	v_and_b32_e32 v127, 0xffff0000, v113
	v_pk_fma_f32 v[116:117], v[116:117], v[124:125], v[120:121]
	v_pk_fma_f32 v[122:123], v[118:119], v[126:127], v[122:123]
	v_mul_f32_e32 v120, 0xbfb8aa3b, v116
	v_mul_f32_e32 v118, 0xbfb8aa3b, v122
	v_exp_f32_e32 v124, v120
	v_mul_f32_e32 v120, 0xbfb8aa3b, v117
	v_exp_f32_e32 v118, v118
	v_mul_f32_e32 v119, 0xbfb8aa3b, v123
	v_exp_f32_e32 v125, v120
	v_exp_f32_e32 v119, v119
	v_add_f32_e32 v118, 1.0, v118
	v_add_f32_e32 v124, 1.0, v124
	v_add_f32_e32 v125, 1.0, v125
	v_rcp_f32_e32 v126, v118
	v_add_f32_e32 v118, 1.0, v119
	v_rcp_f32_e32 v124, v124
	v_rcp_f32_e32 v125, v125
	v_rcp_f32_e32 v127, v118
	v_pk_mul_f32 v[120:121], v[184:185], v[162:163] op_sel_hi:[0,1]
; #define LAS __attribute__((address_space(3)))
; DI unsigned pk2(float lo, float hi) { f32x2 v = {lo, hi}; bf16x2_t b = __builtin_convertvector(v, bf16x2_t); return __builtin_bit_cast(unsigned, b); }
; DI void lds_barrier() { asm volatile("s_waitcnt lgkmcnt(0)" ::: "memory"); __builtin_amdgcn_s_barrier(); asm volatile("" ::: "memory"); }
; DI void dn_intra(const Params& p, LAS unsigned char* L, int tid_in, int wave, int bid, int G, bool dry) {
;     ...
;           const float kb = beta * __expf(gcr);
; #pragma unroll
;           for (int e4 = 0; e4 < 4; ++e4) { *(LAS f32x4*)(RHS + r * DN_RST + 128 + sub * 16 + e4 * 4) = (f32x4){kv[4 * e4] * kb, kv[4 * e4 + 1] * kb, kv[4 * e4 + 2] * kb, kv[4 * e4 + 3] * kb};
;               *(LAS f32x4*)(RHS + r * DN_RST + sub * 16 + e4 * 4) = (f32x4){vv[4 * e4] * beta, vv[4 * e4 + 1] * beta, vv[4 * e4 + 2] * beta, vv[4 * e4 + 3] * beta}; } }
;         lds_barrier();
;         asm volatile("" : "+v"(tid)); lane = tid & 63;
;         { const float eq = __expf(gcr), ek = __expf(gl - gcr);
;           u32x4 w0, w1; w0.x = pk2(qv[0] * eq, qv[1] * eq); w0.y = pk2(qv[2] * eq, qv[3] * eq); w0.z = pk2(qv[4] * eq, qv[5] * eq); w0.w = pk2(qv[6] * eq, qv[7] * eq);
;           w1.x = pk2(qv[8] * eq, qv[9] * eq); w1.y = pk2(qv[10] * eq, qv[11] * eq); w1.z = pk2(qv[12] * eq, qv[13] * eq); w1.w = pk2(qv[14] * eq, qv[15] * eq);
;           bf16_t* q = PRE + (size_t)(row0 + r) * DNQ + h * 128 + sub * 16; if (!dry) { *(u32x4*)q = w0; *(u32x4*)(q + 8) = w1; }
;           w0.x = pk2(kv[0] * ek, kv[1] * ek); w0.y = pk2(kv[2] * ek, kv[3] * ek); w0.z = pk2(kv[4] * ek, kv[5] * ek); w0.w = pk2(kv[6] * ek, kv[7] * ek);
;           w1.x = pk2(kv[8] * ek, kv[9] * ek); w1.y = pk2(kv[10] * ek, kv[11] * ek); w1.z = pk2(kv[12] * ek, kv[13] * ek); w1.w = pk2(kv[14] * ek, kv[15] * ek);
;           if (!dry) { *(u32x4*)(q + 1024) = w0; *(u32x4*)(q + 1024 + 8) = w1; }
;           if (tid == 0) GL[u] = __expf(gl); }
	v_pk_mul_f32 v[118:119], v[184:185], v[164:165] op_sel_hi:[0,1]
	ds_write_b128 v188, v[118:121] offset:544
	v_pk_mul_f32 v[116:117], v[116:117], v[124:125]
	v_pk_mul_f32 v[118:119], v[122:123], v[126:127]
	v_pk_mul_f32 v[116:117], v[180:181], v[116:117] op_sel_hi:[0,1]
	v_pk_mul_f32 v[118:119], v[180:181], v[118:119] op_sel_hi:[0,1]
	ds_write_b128 v188, v[116:119] offset:32
	v_lshlrev_b32_e32 v116, 16, v90
	v_and_b32_e32 v117, 0xffff0000, v90
	v_pk_fma_f32 v[12:13], v[12:13], v[116:117], 0 op_sel_hi:[1,1,0]
	v_lshlrev_b32_e32 v116, 16, v98
	v_and_b32_e32 v117, 0xffff0000, v98
	v_pk_fma_f32 v[8:9], v[8:9], v[116:117], v[12:13]
	v_lshlrev_b32_e32 v12, 16, v106
	v_and_b32_e32 v13, 0xffff0000, v106
	v_pk_fma_f32 v[4:5], v[4:5], v[12:13], v[8:9]
	v_lshlrev_b32_e32 v12, 16, v91
	v_and_b32_e32 v13, 0xffff0000, v91
	v_pk_fma_f32 v[12:13], v[14:15], v[12:13], 0 op_sel_hi:[1,1,0]
	v_lshlrev_b32_e32 v14, 16, v99
	v_and_b32_e32 v15, 0xffff0000, v99
	v_pk_fma_f32 v[10:11], v[10:11], v[14:15], v[12:13]
	v_lshlrev_b32_e32 v12, 16, v107
	v_and_b32_e32 v13, 0xffff0000, v107
	v_lshlrev_b32_e32 v8, 16, v114
	v_and_b32_e32 v9, 0xffff0000, v114
	v_pk_fma_f32 v[6:7], v[6:7], v[12:13], v[10:11]
	v_lshlrev_b32_e32 v10, 16, v115
	v_and_b32_e32 v11, 0xffff0000, v115
	v_pk_fma_f32 v[0:1], v[0:1], v[8:9], v[4:5]
	v_pk_fma_f32 v[6:7], v[2:3], v[10:11], v[6:7]
	v_mul_f32_e32 v4, 0xbfb8aa3b, v0
	v_mul_f32_e32 v2, 0xbfb8aa3b, v6
	v_exp_f32_e32 v8, v4
	v_mul_f32_e32 v4, 0xbfb8aa3b, v1
	v_exp_f32_e32 v2, v2
	v_mul_f32_e32 v3, 0xbfb8aa3b, v7
	v_exp_f32_e32 v9, v4
	v_exp_f32_e32 v3, v3
	v_add_f32_e32 v2, 1.0, v2
	v_add_f32_e32 v8, 1.0, v8
	v_add_f32_e32 v9, 1.0, v9
	v_rcp_f32_e32 v10, v2
	v_add_f32_e32 v2, 1.0, v3
	v_rcp_f32_e32 v8, v8
	v_rcp_f32_e32 v9, v9
	v_rcp_f32_e32 v11, v2
	v_pk_mul_f32 v[4:5], v[184:185], v[66:67] op_sel_hi:[0,1]
	v_pk_mul_f32 v[2:3], v[184:185], v[158:159] op_sel_hi:[0,1]
	ds_write_b128 v188, v[2:5] offset:560
	v_pk_mul_f32 v[0:1], v[0:1], v[8:9]
	v_pk_mul_f32 v[2:3], v[6:7], v[10:11]
	v_pk_mul_f32 v[0:1], v[180:181], v[0:1] op_sel_hi:[0,1]
	v_pk_mul_f32 v[2:3], v[180:181], v[2:3] op_sel_hi:[0,1]
	ds_write_b128 v188, v[0:3] offset:48
	v_sub_f32_e32 v0, v181, v190
	v_mul_f32_e32 v0, 0x3fb8aa3b, v0
	v_exp_f32_e32 v8, v0
	v_pk_mul_f32 v[0:1], v[160:161], v[182:183] op_sel_hi:[1,0]
	v_pk_mul_f32 v[2:3], v[156:157], v[182:183] op_sel_hi:[1,0]
	v_cvt_pk_bf16_f32 v0, v0, v1
	v_cvt_pk_bf16_f32 v1, v2, v3
	v_pk_mul_f32 v[2:3], v[154:155], v[182:183] op_sel_hi:[1,0]
	v_pk_mul_f32 v[4:5], v[152:153], v[182:183] op_sel_hi:[1,0]
	v_cvt_pk_bf16_f32 v2, v2, v3
	v_cvt_pk_bf16_f32 v3, v4, v5
	v_pk_mul_f32 v[4:5], v[150:151], v[182:183] op_sel_hi:[1,0]
	v_pk_mul_f32 v[6:7], v[178:179], v[182:183] op_sel_hi:[1,0]
	v_cvt_pk_bf16_f32 v4, v4, v5
	v_cvt_pk_bf16_f32 v5, v6, v7
	v_pk_mul_f32 v[6:7], v[176:177], v[182:183] op_sel_hi:[1,0]
	v_pk_mul_f32 v[10:11], v[174:175], v[182:183] op_sel_hi:[1,0]
	v_cvt_pk_bf16_f32 v6, v6, v7
	v_cvt_pk_bf16_f32 v7, v10, v11
	v_add_u32_e32 v9, s19, v189
	v_mov_b64_e32 v[10:11], s[52:53]
	v_mad_i64_i32 v[10:11], s[4:5], v9, s3, v[10:11]
	v_lshl_add_u64 v[10:11], v[10:11], 0, v[64:65]
	s_waitcnt lgkmcnt(0)
	s_barrier
	global_store_dwordx4 v[10:11], v[0:3], off
	global_store_dwordx4 v[10:11], v[4:7], off offset:16
	v_cmp_eq_u32_e32 vcc, 0, v187
	v_pk_mul_f32 v[0:1], v[8:9], v[172:173] op_sel_hi:[0,1]
	v_pk_mul_f32 v[2:3], v[8:9], v[170:171] op_sel_hi:[0,1]
	v_cvt_pk_bf16_f32 v0, v0, v1
	v_cvt_pk_bf16_f32 v1, v2, v3
	v_pk_mul_f32 v[2:3], v[8:9], v[168:169] op_sel_hi:[0,1]
	v_pk_mul_f32 v[4:5], v[8:9], v[166:167] op_sel_hi:[0,1]
	v_cvt_pk_bf16_f32 v2, v2, v3
	v_cvt_pk_bf16_f32 v3, v4, v5
	v_pk_mul_f32 v[4:5], v[8:9], v[164:165] op_sel_hi:[0,1]
	v_pk_mul_f32 v[6:7], v[8:9], v[162:163] op_sel_hi:[0,1]
	v_cvt_pk_bf16_f32 v4, v4, v5
	v_cvt_pk_bf16_f32 v5, v6, v7
	v_pk_mul_f32 v[6:7], v[8:9], v[158:159] op_sel_hi:[0,1]
	v_pk_mul_f32 v[8:9], v[8:9], v[66:67] op_sel_hi:[0,1]
	v_cvt_pk_bf16_f32 v6, v6, v7
	v_cvt_pk_bf16_f32 v7, v8, v9
	global_store_dwordx4 v[10:11], v[0:3], off offset:2048
	global_store_dwordx4 v[10:11], v[4:7], off offset:2064
	s_and_saveexec_b64 s[4:5], vcc
	s_cbranch_execz .LBB0_918
	v_mul_f32_e32 v0, 0x3fb8aa3b, v181
	s_ashr_i32 s1, s0, 31
	v_exp_f32_e32 v2, v0
	s_lshl_b64 s[6:7], s[0:1], 2
	s_add_u32 s6, s17, s6
	s_addc_u32 s7, s18, s7
	v_mov_b64_e32 v[0:1], s[6:7]
	global_store_dword v[0:1], v2, off

; DI void rowinfo(int row, int& s, int& b, int& t) { if (row < MP) { s = 0; b = row >> 12; t = row & 4095; } else { const int r = row - MP; s = 1; b = r >> 6; t = r & 63; } }
; DI void lds_barrier() { asm volatile("s_waitcnt lgkmcnt(0)" ::: "memory"); __builtin_amdgcn_s_barrier(); asm volatile("" ::: "memory"); }
; DI void dn_intra(const Params& p, LAS unsigned char* L, int tid_in, int wave, int bid, int G, bool dry) {
;     ...
;     u32x4 xr[3][4][2];
;     if ((bid >> 3) < NSEG) DN_PREFETCH(bid >> 3, tid_in);
;     for (int seg = (bid >> 3); seg < NSEG; seg += ngrp) {
;         if ((G >> 3) == 0 && (bid != 0)) break;
;         const int u = seg * 8 + h, row0 = seg * 64;
;         int s, b, t0; rowinfo(row0, s, b, t0);
;         int tid = tid_in; asm volatile("" : "+v"(tid)); int lane = tid & 63;
;         const int r = tid >> 3, sub = tid & 7;
;         if (wave == 0) {
;             const float a = AB[(size_t)(row0 + lane) * 16 + h], bq = AB[(size_t)(row0 + lane) * 16 + 8 + h];
;     ...
;         lds_barrier();
;         asm volatile("" : "+v"(tid)); lane = tid & 63;
;         asm volatile("" : "+v"(tid));
;         if (seg + ngrp < NSEG) DN_PREFETCH(seg + ngrp, tid);
.LBB0_986:
	v_readlane_b32 s0, v253, 14
	s_add_i32 s13, s13, s0
	s_waitcnt lgkmcnt(0)
	s_barrier
	s_cmpk_gt_i32 s13, 0x207
	s_cselect_b64 s[28:29], -1, 0
	s_and_b64 vcc, exec, s[28:29]
	s_cbranch_vccnz .LBB0_1069
	s_lshl_b32 s10, s13, 6
	v_and_b32_e32 v222, 63, v187
	v_or_b32_e32 v222, s10, v222
	v_ashrrev_i32_e32 v223, 31, v222
	v_lshlrev_b64 v[222:223], 6, v[222:223]
	v_lshl_add_u64 v[222:223], s[50:51], 0, v[222:223]
	global_load_dword v224, v[222:223], off
	global_load_dword v225, v[222:223], off offset:32
	s_cmpk_gt_i32 s13, 0x1ff
	s_cselect_b64 s[0:1], -1, 0
	s_add_i32 s4, s10, 0xffff8000
	s_lshr_b32 s4, s4, 6
	s_ashr_i32 s5, s13, 6
	s_cmpk_lt_i32 s13, 0x200
	s_cselect_b32 s6, 0xfc0, 0
	s_cselect_b32 s7, s5, s4
	s_and_b32 s4, s6, s10
	v_lshlrev_b32_e32 v1, 4, v187
	v_and_b32_e32 v1, 0x70, v1
	s_cmp_lg_u32 s4, 0
	s_cselect_b64 s[4:5], -1, 0
	v_or_b32_e32 v8, s14, v1
	v_readlane_b32 s60, v253, 47
	v_ashrrev_i32_e32 v0, 3, v187
	s_add_i32 s6, s13, -1
	v_lshlrev_b32_e32 v64, 1, v8
	v_lshlrev_b32_e32 v2, 2, v8
	v_mov_b32_e32 v3, v65
	v_readlane_b32 s66, v253, 53
	v_readlane_b32 s67, v253, 54
	v_cndmask_b32_e64 v1, 0, 1, s[4:5]
	s_mul_hi_i32 s31, s6, 3
	s_mul_i32 s30, s6, 3
	s_mul_i32 s8, s7, 3
	v_lshl_add_u64 v[4:5], s[46:47], 0, v[64:65]
	v_lshl_add_u64 v[2:3], s[66:67], 0, v[2:3]
	v_cmp_gt_i32_e64 s[40:41], 3, v0
	v_cmp_ne_u32_e64 s[36:37], 1, v1
	v_readlane_b32 s61, v253, 48
	v_readlane_b32 s62, v253, 49
	v_readlane_b32 s63, v253, 50
	v_readlane_b32 s64, v253, 51
	v_readlane_b32 s65, v253, 52
	v_readlane_b32 s68, v253, 55
	v_readlane_b32 s69, v253, 56
	v_readlane_b32 s70, v253, 57
	v_readlane_b32 s71, v253, 58
	v_readlane_b32 s72, v253, 59
	v_readlane_b32 s73, v253, 60
	v_readlane_b32 s74, v253, 61
	v_readlane_b32 s75, v253, 62
	s_and_saveexec_b64 s[4:5], s[40:41]
	s_xor_b64 s[4:5], exec, s[4:5]
	s_cbranch_execz .LBB0_995
	s_and_b64 vcc, exec, s[36:37]
	s_cbranch_vccnz .LBB0_991
	v_ashrrev_i32_e32 v1, 31, v0
	v_lshl_add_u64 v[6:7], s[30:31], 0, v[0:1]
	v_mad_u64_u32 v[10:11], s[6:7], v6, s3, v[4:5]
	v_mov_b32_e32 v6, v11
	v_mad_u64_u32 v[6:7], s[6:7], v7, s3, v[6:7]
	v_mov_b32_e32 v11, v6
	global_load_dwordx4 v[16:19], v[10:11], off
	global_load_dwordx4 v[20:23], v[10:11], off offset:16
	s_cbranch_execz .LBB0_992
	s_branch .LBB0_995
